# six grid-barrier sites rewritten by hand: per-XCC arrival, XCD leader writeback, last leader fans release flags out to all XCCs, acquire invalidate issued before polling
# speedup vs baseline: 1.0400x; 1.0074x over previous
; #define LAS __attribute__((address_space(3)))
; __device__ __forceinline__ unsigned xb_add(unsigned* p, unsigned v) { return __hip_atomic_fetch_add(p, v, __ATOMIC_RELAXED, __HIP_MEMORY_SCOPE_AGENT); }
; __device__ __forceinline__ unsigned xb_xcc_id() { return (unsigned)__builtin_amdgcn_s_getreg((3 << 11) | 20) & 0xFu; }
; __device__ __forceinline__ XcdBarrier xcd_barrier_post(unsigned* bar, volatile LAS unsigned* st) {
;     XcdBarrier b; b.bar = bar; b.x = xb_xcc_id(); b.st = st;
;     if (threadIdx.x == 0) (void)xb_add(&bar[XB_XCNT(b.x)], 1u);
;     return b;
; }
; __global__ void __launch_bounds__(NTHREADS, 2) mega(Params p) {
;     extern __shared__ __attribute__((aligned(16))) unsigned char lds_raw[];
;     LAS unsigned char* lds = (LAS unsigned char*)lds_raw;
;     cg::grid_group grid = cg::this_grid();
;     int tid = threadIdx.x; const int G = gridDim.x;
;     ...
;     unsigned char* ws = p.ws;
;     volatile LAS unsigned* xst = (volatile LAS unsigned*)(lds + LDS_BYTES - 64);
;     if (tid < 16) xst[tid] = 0u;
;     __syncthreads();
;     XcdBarrier xb = xcd_barrier_post((unsigned*)(ws + WS_CTL) + 1024, xst);
_Z4mega6Params:
	s_load_dwordx8 s[84:91], s[0:1], 0x80
	s_load_dword s92, s[0:1], 0xa0
	s_add_u32 s18, s0, 0x98
	v_and_b32_e32 v220, 0x3ff, v0
	s_addc_u32 s19, s1, 0
	v_cmp_gt_u32_e32 vcc, 16, v220
	s_and_saveexec_b64 s[4:5], vcc
	v_lshl_add_u32 v1, v220, 2, 0
	v_add_u32_e32 v1, 0x23fc0, v1
	v_mov_b32_e32 v2, 0
	ds_write_b32 v1, v2
	s_or_b64 exec, exec, s[4:5]
	s_waitcnt lgkmcnt(0)
	s_barrier
	s_add_u32 s36, s88, 0x1000
	s_getreg_b32 s3, hwreg(HW_REG_XCC_ID, 0, 4)
	s_addc_u32 s37, s89, 0
	s_and_b32 s93, s3, 15
	s_and_b32 s99, s3, 15
	s_mov_b32 s98, 0
	s_mov_b32 s100, 0
	v_cmp_eq_u32_e64 s[6:7], 0, v220
	s_mov_b64 s[4:5], exec
	s_nop 0
	v_writelane_b32 v252, s6, 0
	s_nop 1
	v_writelane_b32 v252, s7, 1
	s_and_b64 s[6:7], s[4:5], s[6:7]
	s_mov_b64 exec, s[6:7]
	s_cbranch_execz .LBB0_5
	s_mov_b64 s[6:7], exec
	v_mbcnt_lo_u32_b32 v1, s6, 0
	v_mbcnt_hi_u32_b32 v1, s7, v1
	v_cmp_eq_u32_e32 vcc, 0, v1
	s_and_b64 s[8:9], exec, vcc
	s_mov_b64 exec, s[8:9]
	s_cbranch_execz .LBB0_5
	s_lshl_b32 s8, s93, 8
	s_bcnt1_i32_b64 s6, s[6:7]
	v_mov_b32_e32 v1, s8
	v_mov_b32_e32 v2, s6
	global_atomic_add v1, v2, s[36:37] offset:1024

; __global__ void __launch_bounds__(NTHREADS, 2) mega(Params p) {
;     ...
;     grid.sync();
;     const float* GS = (const float*)(ws + WS_GS); float* RS = (float*)(ws + WS_RS);
;     for (int l = 0; l < 2; ++l) {
;         const float* modl = (const float*)(ws + WS_MOD) + (size_t)l * 9 * 6144;
;         const float* xs = l == 0 ? p.x : p.out; const float* cs = l == 0 ? p.ctx : XC;
;         const int Mres = l == 0 ? MT : MX;
.LBB0_130:
	s_or_b64 exec, exec, s[0:1]
	v_lshrrev_b32_e32 v1, 20, v0
	v_lshrrev_b32_e32 v0, 10, v0
	v_or_b32_e32 v0, v0, v1
	s_movk_i32 s0, 0x3ff
	v_and_or_b32 v0, v0, s0, v220
	v_cmp_eq_u32_e32 vcc, 0, v0
	s_waitcnt vmcnt(0) lgkmcnt(0)
	s_barrier
	s_and_saveexec_b64 s[0:1], vcc
	s_xor_b64 s[0:1], exec, s[0:1]
	s_cbranch_execz .LBB0_140
	buffer_wbl2 sc1
	s_waitcnt vmcnt(0)
	s_add_u32 s4, s88, 0x5000
	s_addc_u32 s5, s89, 0
	v_mov_b32_e32 v2, 0
	v_mov_b32_e32 v3, 1
	global_atomic_add v0, v2, v3, s[4:5] sc0
	s_lshl_b32 s7, s93, 8
	s_add_i32 s7, s7, 0x100
	v_mov_b32_e32 v4, s7
	s_waitcnt vmcnt(0)
	v_readfirstlane_b32 s6, v0
	s_nop 3
	s_add_i32 s6, s6, 1
	s_cmp_lg_u32 s6, s90
	s_cbranch_scc1 .Lgsync_spin
	global_store_dword v2, v3, s[4:5] offset:256 sc0 sc1
	global_store_dword v2, v3, s[4:5] offset:512 sc0 sc1
	global_store_dword v2, v3, s[4:5] offset:768 sc0 sc1
	global_store_dword v2, v3, s[4:5] offset:1024 sc0 sc1
	global_store_dword v2, v3, s[4:5] offset:1280 sc0 sc1
	global_store_dword v2, v3, s[4:5] offset:1536 sc0 sc1
	global_store_dword v2, v3, s[4:5] offset:1792 sc0 sc1
	global_store_dword v2, v3, s[4:5] offset:2048 sc0 sc1
	global_store_dword v2, v3, s[4:5] offset:2304 sc0 sc1
	global_store_dword v2, v3, s[4:5] offset:2560 sc0 sc1
	global_store_dword v2, v3, s[4:5] offset:2816 sc0 sc1
	global_store_dword v2, v3, s[4:5] offset:3072 sc0 sc1
	global_store_dword v2, v3, s[4:5] offset:3328 sc0 sc1
	global_store_dword v2, v3, s[4:5] offset:3584 sc0 sc1
	global_store_dword v2, v3, s[4:5] offset:3840 sc0 sc1
	s_add_u32 s8, s4, 0x1000
	s_addc_u32 s9, s5, 0
	global_store_dword v2, v3, s[8:9] sc0 sc1
	s_waitcnt vmcnt(0)
	buffer_inv sc1
.Lgsync_spin:
	global_load_dword v0, v4, s[4:5] sc1
	s_waitcnt vmcnt(0)
	v_cmp_eq_u32_e32 vcc, 0, v0
	s_cbranch_vccz .Lgsync_done
	s_sleep 1
	s_branch .Lgsync_spin
.Lgsync_done:
	s_waitcnt vmcnt(0)
.LBB0_140:
	v_writelane_b32 v252, s12, 19
	s_nop 1
	v_writelane_b32 v252, s13, 20
	v_writelane_b32 v252, s57, 21
	v_writelane_b32 v252, s56, 22
	s_or_b64 exec, exec, s[0:1]
	s_add_u32 s12, s88, 0x7c00000
	s_addc_u32 s13, s89, 0
	s_add_u32 s69, s88, 0xc000000
	s_addc_u32 s51, s89, 0
	s_add_u32 s0, s88, 0x18d00000
	v_writelane_b32 v252, s0, 23
	s_addc_u32 s0, s89, 0
	v_writelane_b32 v252, s0, 24
	s_add_u32 s0, s88, 0x7400000
	s_addc_u32 s1, s89, 0
	v_writelane_b32 v252, s0, 25
	s_mov_b32 s77, 0
	v_mov_b32_e32 v187, 0
	v_writelane_b32 v252, s1, 26
	s_add_u32 s0, s88, 0x3500000
	s_addc_u32 s1, s89, 0
	v_writelane_b32 v252, s0, 27
	s_add_u32 s34, s88, 0x100000
	s_addc_u32 s35, s89, 0
	v_writelane_b32 v252, s1, 28
	s_lshl_b32 s0, s2, 3
	s_lshl_b32 s40, s90, 3
	s_cmpk_lt_i32 s2, 0x9c
	v_writelane_b32 v252, s0, 29
	s_cselect_b64 s[0:1], -1, 0
	v_writelane_b32 v252, s0, 30
	v_mov_b32_e32 v221, 0x358637bd
	v_mov_b32_e32 v222, 1
	v_writelane_b32 v252, s1, 31
	s_add_u32 s0, s88, 0x780000
	s_addc_u32 s1, s89, 0
	v_writelane_b32 v252, s0, 32
	v_mov_b64_e32 v[190:191], 0x3b7
	v_mov_b32_e32 v231, 0x15900000
	v_writelane_b32 v252, s1, 33
	s_add_u32 s0, s88, 0x3680000
	s_addc_u32 s1, s89, 0
	v_writelane_b32 v252, s0, 34
	v_mov_b32_e32 v232, 0x13700000
	v_mov_b32_e32 v233, 0x88000
	v_writelane_b32 v252, s1, 35
	s_add_u32 s0, s88, 0x3600000
	v_writelane_b32 v252, s0, 36
	s_addc_u32 s0, s89, 0
	v_writelane_b32 v252, s0, 37
	s_add_u32 s0, s88, 0x1200
	s_addc_u32 s1, s89, 0
	s_add_u32 s94, s88, 0x1400
	s_addc_u32 s95, s89, 0
	s_add_u32 s14, s88, 0x1500
	v_writelane_b32 v252, s0, 38
	s_addc_u32 s15, s89, 0
	s_mov_b32 s68, 0x38e38e39
	v_writelane_b32 v252, s1, 39
	s_add_u32 s0, s88, 0x1600
	s_addc_u32 s1, s89, 0
	v_writelane_b32 v252, s0, 40
	s_movk_i32 s46, 0x4000
	s_movk_i32 s20, 0xe00
	v_writelane_b32 v252, s1, 41
	s_add_u32 s0, s88, 0x1700
	s_addc_u32 s1, s89, 0
	v_writelane_b32 v252, s0, 42
	s_mov_b32 s21, 0xc0135761
	s_mov_b32 s22, 0x18d00000
	v_writelane_b32 v252, s1, 43
	s_add_u32 s0, s88, 0x1800
	s_addc_u32 s1, s89, 0
	v_writelane_b32 v252, s0, 44
	s_mov_b32 s23, 0x18d01000
	s_mov_b32 s24, 0x66666667
	v_writelane_b32 v252, s1, 45
	s_add_u32 s0, s88, 0x1900
	s_addc_u32 s1, s89, 0
	v_writelane_b32 v252, s0, 46
	s_movk_i32 s25, 0xffb0
	s_movk_i32 s26, 0xfd80
	v_writelane_b32 v252, s1, 47
	s_add_u32 s0, s88, 0x1a00
	s_addc_u32 s1, s89, 0
	v_writelane_b32 v252, s0, 48
	s_movk_i32 s27, 0x1100
	s_mov_b64 s[80:81], 0x2000
	v_writelane_b32 v252, s1, 49
	s_add_u32 s0, s88, 0x1b00
	s_addc_u32 s1, s89, 0
	v_writelane_b32 v252, s0, 50
	s_mov_b64 s[44:45], 0x80
	s_mov_b32 s84, 0x3c800000
	v_writelane_b32 v252, s1, 51
	s_add_u32 s0, s88, 0x1c00
	s_addc_u32 s1, s89, 0
	v_writelane_b32 v252, s0, 52
	s_mov_b64 s[96:97], 0x10000
	s_mov_b32 s50, 0x3e38aa3b
	v_writelane_b32 v252, s1, 53
	s_add_u32 s0, s88, 0x1d00
	s_addc_u32 s1, s89, 0
	v_writelane_b32 v252, s0, 54
	s_mov_b32 s82, s77
	s_barrier
; __device__ __forceinline__ unsigned xb_ld(unsigned* p)              { return __hip_atomic_load(p, __ATOMIC_RELAXED, __HIP_MEMORY_SCOPE_AGENT); }
; #define GEMMCALL if (0)
; #define FRESH_TID() asm volatile("" : "+v"(tid))
; #define GBAR() do { for (int rep = 0; rep < REP_BAR; ++rep) xcd_barrier(xb); } while (0)
; __device__ __forceinline__ void xcd_barrier_complete(unsigned* bar, unsigned x, unsigned& nloc, unsigned& nx) {
;     ...
;         for (unsigned j = 0; j < 16; ++j) { const unsigned c = xb_ld(&bar[XB_XCNT(j)]); sum += c; cnt += (c > 0u) ? 1u : 0u; mine = (j == x) ? c : mine; }
;         if (sum == G) break;
;         __builtin_amdgcn_s_sleep(1);
;         if ((++sp & 255u) == 0u) { if (xb_ld(&bar[XB_TMO])) break; if (sp > XB_SPIN_CAP) { atomicAdd(&bar[XB_TMO], 1u); break; } }
;     }
;     nloc = mine > 0u ? mine : 1u; nx = cnt > 0u ? cnt : 1u;
; __global__ void __launch_bounds__(NTHREADS, 2) mega(Params p) {
;     ...
;     const float* GS = (const float*)(ws + WS_GS); float* RS = (float*)(ws + WS_RS);
;     for (int l = 0; l < 2; ++l) {
;         const float* modl = (const float*)(ws + WS_MOD) + (size_t)l * 9 * 6144;
;         const float* xs = l == 0 ? p.x : p.out; const float* cs = l == 0 ? p.ctx : XC;
;         const int Mres = l == 0 ? MT : MX;
;         if (l == 0) {
;             for (int rep = 0; rep < REP_NORM; ++rep) { FRESH_TID(); norm_phase(xs, cs, p.g1 + l * DM, modl, 0, A1, MT, tid); }
;             FRESH_TID(); aux_phase(p, lds, tid);
;             GBAR();
;         }
;         {
;             pg8::Gemm g{A1, (const bf16_t*)(ws + WS_WIN) + (size_t)l * NIN * 1024, MT, NIN, 1024}; pg8::StaticOrder S; S.init(MT, NIN, G, (int)blockIdx.x);
;             if (l == 0) { EpiStore<0> E{PX, NIN, 256}; GEMMCALL pg8::gemm_phase<EpiStore<0>, pg8::StaticOrder, true, true>(lds, g, S, E); }
;             else { EpiStoreN<0> E{PX, NIN, RS + MT, (const float*)(ws + WS_SHW) + 131072, NIN}; GEMMCALL pg8::gemm_phase<EpiStoreN<0>, pg8::StaticOrder, true, true>(lds, g, S, E); }
	v_writelane_b32 v252, s1, 55
	s_add_u32 s0, s88, 0x1e00
	s_addc_u32 s1, s89, 0
	v_writelane_b32 v252, s0, 56
	s_nop 1
	v_writelane_b32 v252, s1, 57
	s_add_u32 s0, s88, 0x1f00
	s_addc_u32 s1, s89, 0
	v_writelane_b32 v252, s0, 58
	s_nop 1
	v_writelane_b32 v252, s1, 59
	s_add_u32 s0, s88, 0x2000
	s_addc_u32 s1, s89, 0
	v_writelane_b32 v252, s0, 60
	s_nop 1
	v_writelane_b32 v252, s1, 61
	s_add_u32 s0, s88, 0x2100
	s_addc_u32 s1, s89, 0
	v_writelane_b32 v252, s0, 62
	s_nop 1
	v_writelane_b32 v252, s1, 63
	s_add_u32 s0, s88, 0x2200
	s_addc_u32 s1, s89, 0
	v_writelane_b32 v254, s0, 0
	s_nop 1
	v_writelane_b32 v254, s1, 1
	s_add_u32 s0, s88, 0x2300
	s_addc_u32 s1, s89, 0
	v_writelane_b32 v254, s0, 2
	s_cmp_eq_u32 s93, 15
	s_nop 0
	v_writelane_b32 v254, s1, 3
	s_cselect_b64 s[0:1], -1, 0
	v_writelane_b32 v254, s0, 4
	s_cmp_eq_u32 s93, 14
	s_nop 0
	v_writelane_b32 v254, s1, 5
	s_cselect_b64 s[0:1], -1, 0
	v_writelane_b32 v254, s0, 6
	s_cmp_eq_u32 s93, 13
	s_nop 0
	v_writelane_b32 v254, s1, 7
	s_cselect_b64 s[0:1], -1, 0
	v_writelane_b32 v254, s0, 8
	s_cmp_eq_u32 s93, 12
	s_nop 0
	v_writelane_b32 v254, s1, 9
	s_cselect_b64 s[0:1], -1, 0
	v_writelane_b32 v254, s0, 10
	s_cmp_eq_u32 s93, 11
	s_nop 0
	v_writelane_b32 v254, s1, 11
	s_cselect_b64 s[0:1], -1, 0
	v_writelane_b32 v254, s0, 12
	s_cmp_eq_u32 s93, 10
	s_nop 0
	v_writelane_b32 v254, s1, 13
	s_cselect_b64 s[0:1], -1, 0
	v_writelane_b32 v254, s0, 14
	s_cmp_eq_u32 s93, 9
	s_nop 0
	v_writelane_b32 v254, s1, 15
	s_cselect_b64 s[0:1], -1, 0
	v_writelane_b32 v254, s0, 16
	s_cmp_eq_u32 s93, 8
	s_nop 0
	v_writelane_b32 v254, s1, 17
	s_cselect_b64 s[0:1], -1, 0
	v_writelane_b32 v254, s0, 18
	s_cmp_eq_u32 s93, 7
	s_nop 0
	v_writelane_b32 v254, s1, 19
	s_cselect_b64 s[0:1], -1, 0
	v_writelane_b32 v254, s0, 20
	s_cmp_eq_u32 s93, 6
	s_nop 0
	v_writelane_b32 v254, s1, 21
	s_cselect_b64 s[0:1], -1, 0
	v_writelane_b32 v254, s0, 22
	s_cmp_eq_u32 s93, 5
	s_nop 0
	v_writelane_b32 v254, s1, 23
	s_cselect_b64 s[0:1], -1, 0
	v_writelane_b32 v254, s0, 24
	s_cmp_eq_u32 s93, 4
	s_nop 0
	v_writelane_b32 v254, s1, 25
	s_cselect_b64 s[0:1], -1, 0
	v_writelane_b32 v254, s0, 26
	s_cmp_eq_u32 s93, 3
	s_nop 0
	v_writelane_b32 v254, s1, 27
	s_cselect_b64 s[0:1], -1, 0
	v_writelane_b32 v254, s0, 28
	s_cmp_eq_u32 s93, 2
	s_nop 0
	v_writelane_b32 v254, s1, 29
	s_cselect_b64 s[0:1], -1, 0
	v_writelane_b32 v254, s0, 30
	s_cmp_eq_u32 s93, 1
	s_nop 0
	v_writelane_b32 v254, s1, 31
	s_cselect_b64 s[0:1], -1, 0
	v_writelane_b32 v254, s0, 32
	s_cmp_eq_u32 s93, 0
	s_nop 0
	v_writelane_b32 v254, s1, 33
	s_cselect_b64 s[0:1], -1, 0
	v_writelane_b32 v254, s0, 34
	s_nop 1
	v_writelane_b32 v254, s1, 35
	s_lshl_b32 s0, s93, 8
	s_add_u32 s0, s36, s0
	s_addc_u32 s1, s37, 0
	s_add_u32 s4, s0, 0x1400
	s_addc_u32 s5, s1, 0
	v_writelane_b32 v254, s4, 36
	s_add_u32 s0, s0, 0x2400
	s_addc_u32 s1, s1, 0
	v_writelane_b32 v254, s5, 37
	v_writelane_b32 v254, s0, 38
	s_nop 1
	v_writelane_b32 v254, s1, 39
	s_add_u32 s0, s88, 0x4400
	s_addc_u32 s1, s89, 0
	v_writelane_b32 v254, s0, 40
	s_nop 1
	v_writelane_b32 v254, s1, 41
	s_add_u32 s0, s88, 0x4500
	s_addc_u32 s1, s89, 0
	v_writelane_b32 v254, s0, 42
	s_nop 1
	v_writelane_b32 v254, s1, 43
	s_add_u32 s0, s88, 0x3722000
	v_writelane_b32 v254, s0, 44
	s_addc_u32 s0, s89, 0
	s_cmpk_lt_i32 s2, 0x3b8
	v_writelane_b32 v254, s0, 45
	s_cselect_b64 s[0:1], -1, 0
	v_writelane_b32 v254, s0, 46
	s_ashr_i32 s85, s2, 31
	s_ashr_i32 s33, s90, 31
	v_writelane_b32 v254, s1, 47
	s_lshr_b32 s0, s85, 29
	s_add_i32 s0, s2, s0
	s_ashr_i32 s3, s0, 3
	s_and_b32 s0, s0, -8
	s_sub_i32 s11, s2, s0
	s_add_u32 s0, s88, 0x16200000
	s_addc_u32 s1, s89, 0
	v_writelane_b32 v254, s0, 48
	s_nop 1
	v_writelane_b32 v254, s1, 49
	s_add_u32 s0, s88, 0x16b00000
	s_addc_u32 s1, s89, 0
	s_add_u32 s16, s88, 0x18b00000
	v_writelane_b32 v254, s0, 50
	s_addc_u32 s17, s89, 0
	s_nop 0
	v_writelane_b32 v254, s1, 51
	s_add_u32 s0, s88, 0x8000
	v_writelane_b32 v254, s0, 52
	s_addc_u32 s0, s89, 0
	s_cmpk_lt_i32 s2, 0x330
	v_writelane_b32 v254, s0, 53
	s_cselect_b64 s[0:1], -1, 0
	v_writelane_b32 v254, s0, 54
	s_cmpk_lt_i32 s2, 0x100
	s_nop 0
	v_writelane_b32 v254, s1, 55
	s_cselect_b64 s[0:1], -1, 0
	s_add_u32 s42, s88, 0x3300000
	v_writelane_b32 v254, s0, 56
	s_addc_u32 s43, s89, 0
	s_nop 0
	v_writelane_b32 v254, s1, 57
	s_add_u32 s0, s88, 0x1cd00400
	v_writelane_b32 v254, s0, 58
	s_addc_u32 s0, s89, 0
	s_cmp_lt_i32 s2, 8
	v_writelane_b32 v254, s0, 59
	s_cselect_b64 s[0:1], -1, 0
	v_writelane_b32 v254, s0, 60
	s_nop 1
	v_writelane_b32 v254, s1, 61
	s_lshr_b32 s0, s11, 31
	v_writelane_b32 v254, s0, 62
	s_lshl_b32 s0, s11, s0
	s_add_i32 s0, s0, s3
	s_ashr_i32 s1, s0, 31
	s_lshr_b32 s1, s1, 26
	s_add_i32 s1, s0, s1
	s_and_b32 s4, s1, 0xffffffc0
	s_sub_i32 s4, s0, s4
	s_ashr_i32 s0, s1, 6
	s_lshl_b32 s5, s0, 3
	s_sub_i32 s0, 1, s5
	s_min_u32 s6, s0, 8
	s_add_u32 s0, s88, 0x13700000
	v_writelane_b32 v254, s0, 63
	s_addc_u32 s0, s89, 0
	v_writelane_b32 v255, s0, 0
	s_add_u32 s0, s88, 0x15900000
	s_addc_u32 s1, s89, 0
	v_writelane_b32 v255, s0, 1
	v_cvt_f32_ubyte0_e32 v1, s6
	v_cvt_f32_i32_e32 v0, s4
	v_writelane_b32 v255, s1, 2
	s_add_u32 s0, s88, 0x3512000
	v_writelane_b32 v255, s0, 3
	s_addc_u32 s0, s89, 0
	s_cmpk_lt_i32 s2, 0x200
	v_writelane_b32 v255, s0, 4
	s_cselect_b64 s[0:1], -1, 0
	s_lshl_b32 s7, s11, 6
	v_writelane_b32 v255, s0, 5
	s_cmpk_lt_i32 s2, 0x80
	v_rcp_iflag_f32_e32 v2, v1
	v_writelane_b32 v255, s1, 6
	s_cselect_b64 s[0:1], -1, 0
	v_writelane_b32 v255, s0, 7
	v_mul_f32_e32 v2, v0, v2
	v_trunc_f32_e32 v2, v2
	v_writelane_b32 v255, s1, 8
	s_add_u32 s0, s88, 0x1c000000
	v_writelane_b32 v255, s0, 9
	s_addc_u32 s0, s89, 0
	v_writelane_b32 v255, s0, 10
;     __device__ bool next(int i, pg8::Unit& u) const { if (i != 0 || !has) return false; u.pm = pm; u.pn = pn; return true; }
; #define GEMMCALL if (0)
;     __host__ __device__ bool next(int i, Unit& u) const {
;         const long L = (long)i * G + c; if (L >= nwg) return false;
;         int wgid = (int)L; { const int q = nwg / NXCD, r = nwg % NXCD, xcd = wgid % NXCD, off = wgid / NXCD; wgid = (xcd < r ? xcd * (q + 1) : r * (q + 1) + (xcd - r) * q) + off; }
;         const int nig = WGM * nN, gid = wgid / nig, fm = gid * WGM, gsz = (nM - fm) < WGM ? (nM - fm) : WGM;
;         u.pm = fm + ((wgid % nig) % gsz); u.pn = (wgid % nig) / gsz; return true;
; __global__ void __launch_bounds__(NTHREADS, 2) mega(Params p) {
;     ...
;             pg8::Gemm g{A1, (const bf16_t*)(ws + WS_WIN) + (size_t)l * NIN * 1024, MT, NIN, 1024}; pg8::StaticOrder S; S.init(MT, NIN, G, (int)blockIdx.x);
;             if (l == 0) { EpiStore<0> E{PX, NIN, 256}; GEMMCALL pg8::gemm_phase<EpiStore<0>, pg8::StaticOrder, true, true>(lds, g, S, E); }
;             else { EpiStoreN<0> E{PX, NIN, RS + MT, (const float*)(ws + WS_SHW) + 131072, NIN}; GEMMCALL pg8::gemm_phase<EpiStoreN<0>, pg8::StaticOrder, true, true>(lds, g, S, E); }
	s_add_u32 s0, s88, 0x3a00000
	s_addc_u32 s1, s89, 0
	v_writelane_b32 v255, s0, 11
	v_fma_f32 v0, -v2, v1, v0
	s_nop 0
	v_writelane_b32 v255, s1, 12
	s_add_u32 s0, s88, 0x351a000
	s_addc_u32 s1, s89, 0
	v_writelane_b32 v255, s0, 13
	s_nop 1
	v_writelane_b32 v255, s1, 14
	s_add_u32 s0, s88, 0x135000
	s_addc_u32 s1, s89, 0
	v_writelane_b32 v255, s0, 15
	s_cmp_lt_i32 s11, 0
	s_nop 0
	v_writelane_b32 v255, s1, 16
	s_cselect_b64 s[0:1], -1, 0
	v_writelane_b32 v255, s0, 17
	s_nop 1
	v_writelane_b32 v255, s1, 18
	s_and_b64 s[0:1], s[0:1], exec
	s_mul_i32 s0, s11, 0x41
	s_cselect_b32 s7, s0, s7
	s_movk_i32 s0, 0x78
	s_cselect_b32 s0, s0, 0x77
	s_mul_i32 s0, s11, s0
	s_cselect_b32 s8, 0x41, 64
	s_add_i32 s0, s0, s3
	s_mul_hi_i32 s1, s0, 0x92492493
	s_add_i32 s1, s1, s0
	s_lshr_b32 s9, s1, 31
	s_ashr_i32 s1, s1, 5
	s_add_i32 s1, s1, s9
	s_mul_i32 s9, s1, 56
	s_sub_i32 s0, s0, s9
	s_bfe_i32 s9, s0, 0x80000
	s_bfe_u32 s9, s9, 0x3000c
	s_add_i32 s9, s0, s9
	s_and_b32 s10, s9, 0xf8
	s_sub_i32 s0, s0, s10
	s_bfe_i32 s9, s9, 0x80000
	s_lshl_b32 s1, s1, 3
	s_sext_i32_i16 s9, s9
	s_sext_i32_i8 s0, s0
	s_add_i32 s18, s1, s0
	s_ashr_i32 s0, s9, 3
	v_writelane_b32 v255, s0, 19
	s_lshr_b32 s0, s9, 3
	s_bfe_i64 s[0:1], s[0:1], 0x100000
	s_lshl_b64 s[0:1], s[0:1], 19
	v_writelane_b32 v255, s0, 20
	s_ashr_i32 s19, s18, 31
	s_mul_i32 s8, s8, s11
	v_writelane_b32 v255, s1, 21
	s_mov_b32 s0, s18
	v_writelane_b32 v255, s0, 22
	s_nop 1
	v_writelane_b32 v255, s1, 23
	s_lshl_b64 s[0:1], s[18:19], 19
	s_add_u32 s0, s12, s0
	v_writelane_b32 v255, s12, 24
	s_addc_u32 s1, s13, s1
	s_movk_i32 s18, 0x1020
	v_writelane_b32 v255, s13, 25
	s_add_u32 s12, s0, 0x40000
	v_writelane_b32 v255, s0, 26
	s_addc_u32 s13, s1, 0
	s_add_i32 s8, s8, s3
	v_writelane_b32 v255, s1, 27
	s_add_i32 s0, s7, s3
	s_ashr_i32 s1, s0, 31
	s_lshr_b32 s1, s1, 27
	s_add_i32 s1, s0, s1
	s_and_b32 s7, s1, 0xffe0
	s_sub_i32 s0, s0, s7
	s_bfe_i32 s7, s0, 0x80000
	s_bfe_u32 s7, s7, 0x3000c
	s_add_i32 s7, s0, s7
	s_and_b32 s9, s7, 0xf8
	s_sub_i32 s0, s0, s9
	s_ashr_i32 s9, s8, 31
	s_lshr_b32 s9, s9, 27
	s_ashr_i32 s1, s1, 5
	s_add_i32 s9, s8, s9
	s_lshl_b32 s1, s1, 3
	s_sext_i32_i8 s0, s0
	v_writelane_b32 v255, s12, 28
	s_add_i32 s2, s1, s0
	s_ashr_i32 s0, s9, 5
	v_writelane_b32 v255, s13, 29
	s_and_b32 s10, s9, 0xffffffe0
	s_bfe_i32 s7, s7, 0x80000
	s_lshl_b32 s9, s0, 3
	v_writelane_b32 v255, s11, 30
	s_sext_i32_i16 s7, s7
	s_sub_i32 s0, 0x80, s9
	v_writelane_b32 v255, s3, 31
	s_sub_i32 s8, s8, s10
	s_min_i32 s10, s0, 8
	s_ashr_i32 s0, s7, 3
	v_writelane_b32 v255, s0, 32
	s_lshr_b32 s0, s7, 3
	s_bfe_i64 s[0:1], s[0:1], 0x100000
	s_lshl_b64 s[0:1], s[0:1], 21
	v_writelane_b32 v255, s0, 33
	s_ashr_i32 s3, s2, 31
	s_movk_i32 s19, 0x2000
	v_writelane_b32 v255, s1, 34
	s_mov_b32 s0, s2
	v_writelane_b32 v255, s0, 35
	s_nop 1
	v_writelane_b32 v255, s1, 36
	s_lshl_b64 s[0:1], s[2:3], 21
	s_add_u32 s0, s69, s0
	s_addc_u32 s1, s51, s1
	s_add_u32 s2, s0, 0x100000
	v_writelane_b32 v255, s0, 37
	s_addc_u32 s3, s1, 0
	s_nop 0
	v_writelane_b32 v255, s1, 38
	s_ashr_i32 s0, s4, 30
	s_or_b32 s7, s0, 1
	v_cmp_ge_f32_e64 s[0:1], |v0|, v1
	v_cvt_i32_f32_e32 v0, v2
	s_and_b64 s[0:1], s[0:1], exec
	s_cselect_b32 s0, s7, 0
	v_writelane_b32 v255, s2, 39
	v_readfirstlane_b32 s1, v0
	s_add_i32 s0, s1, s0
	s_mul_i32 s1, s0, s6
	s_sub_i32 s1, s4, s1
	s_sext_i32_i8 s1, s1
	s_add_i32 s6, s5, s1
	v_writelane_b32 v255, s3, 40
	s_ashr_i32 s7, s6, 31
	s_bfe_i64 s[4:5], s[0:1], 0x80000
	s_mov_b32 s2, s6
	s_lshl_b64 s[4:5], s[4:5], 18
	v_writelane_b32 v255, s2, 41
	s_lshl_b64 s[6:7], s[6:7], 18
	s_sext_i32_i8 s0, s0
	v_writelane_b32 v255, s3, 42
;     __device__ bool next(int i, pg8::Unit& u) const { if (i != 0 || !has) return false; u.pm = pm; u.pn = pn; return true; }
; #define GEMMCALL if (0)
; #define GBAR() do { for (int rep = 0; rep < REP_BAR; ++rep) xcd_barrier(xb); } while (0)
;     __host__ __device__ bool next(int i, Unit& u) const {
;         const long L = (long)i * G + c; if (L >= nwg) return false;
;         int wgid = (int)L; { const int q = nwg / NXCD, r = nwg % NXCD, xcd = wgid % NXCD, off = wgid / NXCD; wgid = (xcd < r ? xcd * (q + 1) : r * (q + 1) + (xcd - r) * q) + off; }
;         const int nig = WGM * nN, gid = wgid / nig, fm = gid * WGM, gsz = (nM - fm) < WGM ? (nM - fm) : WGM;
;         u.pm = fm + ((wgid % nig) % gsz); u.pn = (wgid % nig) / gsz; return true;
; __global__ void __launch_bounds__(NTHREADS, 2) mega(Params p) {
;     ...
;             pg8::Gemm g{MIX, (const bf16_t*)(ws + WS_WOUT) + (size_t)l * 1024 * KOUT, Mres, 1024, KOUT}; pg8::StaticOrder S; S.init(Mres, 1024, G, (int)blockIdx.x);
;             EpiResid2 E{xs, cs, p.out, XC, modl + 2 * 1024, A1, GS + (size_t)(l * 2 + 1) * 9 * 1024, RS + (size_t)(l * 2) * MT, l == 0 ? 1 : 0};
;             GEMMCALL pg8::gemm_phase<EpiResid2, pg8::StaticOrder, true, true>(lds, g, S, E);
;         }
;         GBAR();
;         {
;             pg8::Gemm g{A1, (const bf16_t*)(ws + WS_W1) + (size_t)l * 4096 * 1024, Mres, DFF, 1024}; pg8::StaticOrder S; S.init(Mres, DFF, G, (int)blockIdx.x);
;             EpiStoreN<1> E{H, DFF, RS + (size_t)(l * 2) * MT, (const float*)(ws + WS_SHW) + (size_t)l * 9 * 4096, 4096};
;             GEMMCALL pg8::gemm_phase<EpiStoreN<1>, pg8::StaticOrder, true, true>(lds, g, S, E);
;         }
;         GBAR();
;         {
;             pg8::Gemm g{H, (const bf16_t*)(ws + WS_W2) + (size_t)l * 1024 * 4096, Mres, 1024, DFF}; pg8::StaticOrder S; S.init(Mres, 1024, G, (int)blockIdx.x);
	s_add_u32 s2, s16, s4
	v_writelane_b32 v255, s16, 43
	s_addc_u32 s3, s17, s5
	s_add_u32 s4, s2, 0x20000
	v_writelane_b32 v255, s17, 44
	s_addc_u32 s5, s3, 0
	v_writelane_b32 v255, s4, 45
	s_mov_b32 s16, 0x800000
	s_movk_i32 s17, 0x1000
	v_writelane_b32 v255, s5, 46
	s_add_u32 s4, s62, s6
	s_addc_u32 s5, s63, s7
	s_add_u32 s6, s4, 0x20000
	v_writelane_b32 v255, s4, 47
	s_addc_u32 s7, s5, 0
	s_nop 0
	v_writelane_b32 v255, s5, 48
	v_writelane_b32 v255, s6, 49
	s_add_u32 s4, s2, 0x20080
	s_nop 0
	v_writelane_b32 v255, s7, 50
	v_writelane_b32 v255, s2, 51
	s_addc_u32 s5, s3, 0
	s_abs_i32 s1, s10
	v_cvt_f32_u32_e32 v0, s1
	v_writelane_b32 v255, s3, 52
	v_writelane_b32 v255, s4, 53
	v_rcp_iflag_f32_e32 v0, v0
	s_nop 0
	v_writelane_b32 v255, s5, 54
	s_sub_i32 s4, 0, s1
	v_mul_f32_e32 v0, 0x4f7ffffe, v0
	v_cvt_u32_f32_e32 v0, v0
	s_nop 0
	v_readfirstlane_b32 s5, v0
	s_mul_i32 s4, s4, s5
	s_mul_hi_u32 s4, s5, s4
	s_add_i32 s5, s5, s4
	s_abs_i32 s4, s8
	s_mul_hi_u32 s5, s4, s5
	s_mul_i32 s6, s5, s1
	s_sub_i32 s4, s4, s6
	s_xor_b32 s6, s8, s10
	s_ashr_i32 s6, s6, 31
	s_add_i32 s7, s5, 1
	s_sub_i32 s11, s4, s1
	s_cmp_ge_u32 s4, s1
	s_cselect_b32 s5, s7, s5
	s_cselect_b32 s4, s11, s4
	s_add_i32 s7, s5, 1
	s_cmp_ge_u32 s4, s1
	s_cselect_b32 s1, s7, s5
	s_xor_b32 s1, s1, s6
	s_sub_i32 s6, s1, s6
	s_mul_i32 s1, s6, s10
	s_sub_i32 s1, s8, s1
	s_add_i32 s4, s9, s1
	s_mov_b32 s2, s4
	v_writelane_b32 v255, s2, 55
	s_ashr_i32 s7, s6, 31
	s_ashr_i32 s5, s4, 31
	v_writelane_b32 v255, s3, 56
	s_mov_b32 s2, s6
	v_writelane_b32 v255, s2, 57
	s_lshl_b64 s[4:5], s[4:5], 21
	v_mbcnt_lo_u32_b32 v0, -1, 0
	v_writelane_b32 v255, s3, 58
	s_lshl_b64 s[2:3], s[6:7], 21
	v_writelane_b32 v255, s2, 59
	v_mbcnt_hi_u32_b32 v223, -1, v0
	v_and_b32_e32 v0, 64, v223
	v_writelane_b32 v255, s3, 60
	s_add_u32 s2, s69, s4
	s_addc_u32 s3, s51, s5
	v_writelane_b32 v255, s0, 61
	s_mul_i32 s0, s91, s92
	s_mul_i32 s91, s0, s90
	s_add_u32 s0, s2, 0x100000
	v_writelane_b32 v255, s2, 62
	s_addc_u32 s1, s3, 0
	s_ashr_i32 s29, s28, 31
	v_writelane_b32 v253, s0, 0
	s_lshl_b64 s[66:67], s[28:29], 2
	s_mov_b64 s[92:93], s[14:15]
	v_writelane_b32 v253, s1, 1
	s_add_u32 s0, s88, 0x16200080
	s_addc_u32 s1, s89, 0
	v_writelane_b32 v253, s0, 2
	v_writelane_b32 v255, s3, 63
	v_add_u32_e32 v224, 64, v0
	v_writelane_b32 v253, s1, 3
	s_add_u32 s0, s88, 0x15902000
	s_addc_u32 s1, s89, 0
	v_writelane_b32 v253, s0, 4
	v_xor_b32_e32 v228, 2, v223
	v_xor_b32_e32 v225, 4, v223
	v_writelane_b32 v253, s1, 5
	s_add_u32 s0, s88, 0x1c100080
	v_writelane_b32 v253, s0, 6
	s_addc_u32 s0, s89, 0
	v_writelane_b32 v253, s0, 7
	s_add_u32 s0, s88, 0x2200100
	v_writelane_b32 v253, s0, 8
	s_addc_u32 s0, s89, 0
	v_writelane_b32 v253, s0, 9
	s_add_i32 s0, 0, 0x23fc0
	v_writelane_b32 v253, s0, 10
	s_add_i32 s0, 0, 0x23fc4
	v_writelane_b32 v253, s0, 11
	s_add_i32 s0, 0, 0x20000
	v_writelane_b32 v253, s0, 12
	s_add_i32 s0, 0, 0x20800
	v_writelane_b32 v253, s0, 13
	s_add_i32 s0, 0, 0x22040
	v_writelane_b32 v253, s0, 14
	s_mov_b32 s0, s28
	v_writelane_b32 v253, s0, 15
	v_xor_b32_e32 v229, 16, v223
	v_xor_b32_e32 v230, 32, v223
	v_writelane_b32 v253, s1, 16
	v_writelane_b32 v253, s34, 17
	s_movk_i32 s14, 0x200
	s_movk_i32 s15, 0x6000
	v_writelane_b32 v253, s35, 18
	v_writelane_b32 v253, s40, 19
	v_writelane_b32 v253, s94, 20
	s_mov_b64 s[4:5], -1
	s_mov_b32 s3, s69
	v_writelane_b32 v253, s95, 21
	v_writelane_b32 v253, s92, 22
	s_nop 1
	v_writelane_b32 v253, s93, 23
	v_writelane_b32 v253, s42, 24
	s_nop 1
	v_writelane_b32 v253, s43, 25
	v_writelane_b32 v253, s91, 26
	v_writelane_b32 v253, s66, 27
	s_nop 1
	v_writelane_b32 v253, s67, 28
	s_branch .LBB0_144

; __device__ __forceinline__ unsigned xb_ld(unsigned* p)              { return __hip_atomic_load(p, __ATOMIC_RELAXED, __HIP_MEMORY_SCOPE_AGENT); }
; __device__ __forceinline__ unsigned xb_add(unsigned* p, unsigned v) { return __hip_atomic_fetch_add(p, v, __ATOMIC_RELAXED, __HIP_MEMORY_SCOPE_AGENT); }
; __device__ __forceinline__ void xcd_barrier_complete(unsigned* bar, unsigned x, unsigned& nloc, unsigned& nx) {
;     const unsigned G = gridDim.x * gridDim.y * gridDim.z;
;     unsigned sum, cnt, mine, sp = 0u;
;     for (;;) {
;         sum = 0u; cnt = 0u; mine = 0u;
; #pragma unroll
;         for (unsigned j = 0; j < 16; ++j) { const unsigned c = xb_ld(&bar[XB_XCNT(j)]); sum += c; cnt += (c > 0u) ? 1u : 0u; mine = (j == x) ? c : mine; }
;         if (sum == G) break;
;         __builtin_amdgcn_s_sleep(1);
;         if ((++sp & 255u) == 0u) { if (xb_ld(&bar[XB_TMO])) break; if (sp > XB_SPIN_CAP) { atomicAdd(&bar[XB_TMO], 1u); break; } }
;     }
;     nloc = mine > 0u ? mine : 1u; nx = cnt > 0u ? cnt : 1u;
; }
; __device__ __forceinline__ void xcd_barrier(const XcdBarrier& b) {
;     asm volatile("s_waitcnt vmcnt(0)" ::: "memory");
;     __syncthreads();
;     if (threadIdx.x == 0) {
;         unsigned* bar = b.bar;
;         __builtin_amdgcn_s_waitcnt(0);
;         unsigned nloc = b.st[0], nx = b.st[1];
;         if (nloc == 0u) { xcd_barrier_complete(bar, b.x, nloc, nx); b.st[0] = nloc; b.st[1] = nx; }
;         const unsigned old = xb_add(&bar[XB_XSUB(b.x)], 1u);
;         const unsigned gen = old / nloc;
;         if (old + 1u == (gen + 1u) * nloc) {
;             __builtin_amdgcn_fence(__ATOMIC_RELEASE, "agent");
;             asm volatile("s_waitcnt vmcnt(0)" ::: "memory");
;             const unsigned og = xb_add(&bar[XB_TOP], 1u);
;             const unsigned tg = og / nx;
;             if (og + 1u == (tg + 1u) * nx) xb_add(&bar[XB_TOPGEN], 1u);
;             else XB_SPIN(xb_ld(&bar[XB_TOPGEN]) == tg, bar);
;             __builtin_amdgcn_fence(__ATOMIC_ACQUIRE, "agent");
;             xb_add(&bar[XB_XGEN(b.x)], 1u);
;             asm volatile("s_waitcnt vmcnt(0)" ::: "memory");
;         } else {
;             XB_SPIN(xb_ld(&bar[XB_XGEN(b.x)]) == gen, bar);
;             __builtin_amdgcn_fence(__ATOMIC_ACQUIRE, "agent");
;             asm volatile("s_waitcnt vmcnt(0)" ::: "memory");
;         }
;     }
;     __syncthreads();
; }
.LBB0_194:
	s_waitcnt vmcnt(0) lgkmcnt(0)
	s_barrier
	s_add_i32 s98, s98, 1
	s_mov_b64 s[0:1], exec
	v_readlane_b32 s6, v252, 0
	v_readlane_b32 s7, v252, 1
	s_and_b64 s[6:7], s[0:1], s[6:7]
	s_mov_b64 exec, s[6:7]
	s_cbranch_execz .LBB0_246
	s_add_u32 s10, s88, 0x9000
	s_addc_u32 s11, s89, 0
	s_cmp_lg_u32 s100, 0
	s_cbranch_scc1 .Lxb_have_0
	s_add_u32 s8, s88, 0x1400
	s_addc_u32 s9, s89, 0
.Lxb_census_0:
	v_mov_b32_e32 v0, 0
	global_load_dword v1, v0, s[8:9] sc1
	global_load_dword v2, v0, s[8:9] offset:256 sc1
	global_load_dword v3, v0, s[8:9] offset:512 sc1
	global_load_dword v4, v0, s[8:9] offset:768 sc1
	global_load_dword v5, v0, s[8:9] offset:1024 sc1
	global_load_dword v6, v0, s[8:9] offset:1280 sc1
	global_load_dword v7, v0, s[8:9] offset:1536 sc1
	global_load_dword v8, v0, s[8:9] offset:1792 sc1
	global_load_dword v9, v0, s[8:9] offset:2048 sc1
	global_load_dword v10, v0, s[8:9] offset:2304 sc1
	global_load_dword v11, v0, s[8:9] offset:2560 sc1
	global_load_dword v12, v0, s[8:9] offset:2816 sc1
	global_load_dword v13, v0, s[8:9] offset:3072 sc1
	global_load_dword v14, v0, s[8:9] offset:3328 sc1
	global_load_dword v15, v0, s[8:9] offset:3584 sc1
	global_load_dword v16, v0, s[8:9] offset:3840 sc1
	s_waitcnt vmcnt(0)
	v_add3_u32 v0, v1, v2, v3
	v_add3_u32 v0, v0, v4, v5
	v_add3_u32 v0, v0, v6, v7
	v_add3_u32 v0, v0, v8, v9
	v_add3_u32 v0, v0, v10, v11
	v_add3_u32 v0, v0, v12, v13
	v_add3_u32 v0, v0, v14, v15
	v_add_u32_e32 v0, v0, v16
	s_nop 0
	v_readfirstlane_b32 s31, v0
	s_nop 3
	s_cmp_eq_u32 s31, s90
	s_cbranch_scc1 .Lxb_cdone_0
	s_sleep 2
	s_branch .Lxb_census_0
.Lxb_cdone_0:
	s_lshl_b32 s6, s99, 8
	v_mov_b32_e32 v0, s6
	global_load_dword v1, v0, s[8:9] sc1
	s_waitcnt vmcnt(0)
	v_readfirstlane_b32 s100, v1
	s_nop 3
.Lxb_have_0:
	s_lshl_b32 s6, s99, 8
	v_mov_b32_e32 v0, s6
	v_mov_b32_e32 v1, 1
	global_atomic_add v2, v0, v1, s[10:11] sc0
	s_mul_i32 s7, s98, s100
	s_waitcnt vmcnt(0)
	v_readfirstlane_b32 s31, v2
	s_nop 3
	s_add_i32 s31, s31, 1
	s_cmp_lg_u32 s31, s7
	s_cbranch_scc1 .Lxb_poll_0
	buffer_wbl2 sc1
	s_waitcnt vmcnt(0)
	v_mov_b32_e32 v3, 0x1000
	v_mov_b32_e32 v4, s100
	global_atomic_add v2, v3, v4, s[10:11] sc0
	s_mul_i32 s7, s98, s90
	s_waitcnt vmcnt(0)
	v_readfirstlane_b32 s31, v2
	s_nop 3
	s_add_i32 s31, s31, s100
	s_cmp_lg_u32 s31, s7
	s_cbranch_scc1 .Lxb_poll_0
	v_mov_b32_e32 v3, 0
	v_mov_b32_e32 v4, s98
	s_add_u32 s8, s10, 0x1100
	s_addc_u32 s9, s11, 0
	global_store_dword v3, v4, s[8:9] sc0 sc1
	global_store_dword v3, v4, s[8:9] offset:256 sc0 sc1
	global_store_dword v3, v4, s[8:9] offset:512 sc0 sc1
	global_store_dword v3, v4, s[8:9] offset:768 sc0 sc1
	global_store_dword v3, v4, s[8:9] offset:1024 sc0 sc1
	global_store_dword v3, v4, s[8:9] offset:1280 sc0 sc1
	global_store_dword v3, v4, s[8:9] offset:1536 sc0 sc1
	global_store_dword v3, v4, s[8:9] offset:1792 sc0 sc1
	global_store_dword v3, v4, s[8:9] offset:2048 sc0 sc1
	global_store_dword v3, v4, s[8:9] offset:2304 sc0 sc1
	global_store_dword v3, v4, s[8:9] offset:2560 sc0 sc1
	global_store_dword v3, v4, s[8:9] offset:2816 sc0 sc1
	global_store_dword v3, v4, s[8:9] offset:3072 sc0 sc1
	global_store_dword v3, v4, s[8:9] offset:3328 sc0 sc1
	global_store_dword v3, v4, s[8:9] offset:3584 sc0 sc1
	global_store_dword v3, v4, s[8:9] offset:3840 sc0 sc1
	s_waitcnt vmcnt(0)
.Lxb_poll_0:
	v_add_u32_e32 v0, 0x1100, v0
	buffer_inv sc1
.Lxb_spin_0:
	global_load_dword v2, v0, s[10:11] sc1
	s_waitcnt vmcnt(0)
	v_cmp_gt_u32_e32 vcc, s98, v2
	s_cbranch_vccz .Lxb_done_0
	s_sleep 1
	s_branch .Lxb_spin_0
.Lxb_done_0:
	s_waitcnt vmcnt(0)
.LBB0_246:
	s_or_b64 exec, exec, s[0:1]
	s_waitcnt lgkmcnt(0)
	s_barrier

; __device__ __forceinline__ unsigned xb_add(unsigned* p, unsigned v) { return __hip_atomic_fetch_add(p, v, __ATOMIC_RELAXED, __HIP_MEMORY_SCOPE_AGENT); }
; __device__ __forceinline__ void xcd_barrier(const XcdBarrier& b) {
;     asm volatile("s_waitcnt vmcnt(0)" ::: "memory");
;     __syncthreads();
;     if (threadIdx.x == 0) {
;         unsigned* bar = b.bar;
;         __builtin_amdgcn_s_waitcnt(0);
;         unsigned nloc = b.st[0], nx = b.st[1];
;         if (nloc == 0u) { xcd_barrier_complete(bar, b.x, nloc, nx); b.st[0] = nloc; b.st[1] = nx; }
;         const unsigned old = xb_add(&bar[XB_XSUB(b.x)], 1u);
.LBB0_282:
	s_waitcnt vmcnt(0) lgkmcnt(0)
	s_barrier
	s_add_i32 s98, s98, 1
	s_mov_b64 s[0:1], exec
	v_readlane_b32 s6, v252, 0
	v_readlane_b32 s7, v252, 1
	s_and_b64 s[6:7], s[0:1], s[6:7]
	v_readlane_b32 s12, v253, 39
	v_readlane_b32 s13, v253, 40
	v_readlane_b32 s28, v253, 14
	s_mov_b64 exec, s[6:7]
	s_cbranch_execz .LBB0_334
	s_add_u32 s10, s88, 0x9000
	s_addc_u32 s11, s89, 0
	s_cmp_lg_u32 s100, 0
	s_cbranch_scc1 .Lxb_have_1
	s_add_u32 s8, s88, 0x1400
	s_addc_u32 s9, s89, 0

; __device__ __forceinline__ unsigned xb_ld(unsigned* p)              { return __hip_atomic_load(p, __ATOMIC_RELAXED, __HIP_MEMORY_SCOPE_AGENT); }
; __device__ __forceinline__ unsigned xb_add(unsigned* p, unsigned v) { return __hip_atomic_fetch_add(p, v, __ATOMIC_RELAXED, __HIP_MEMORY_SCOPE_AGENT); }
; #define XB_SPIN(cond, bar) do { unsigned _sp = 0; while (cond) { __builtin_amdgcn_s_sleep(1); \
;     if ((++_sp & 255u) == 0u) { if (xb_ld(&(bar)[XB_TMO])) break; if (_sp > XB_SPIN_CAP) { atomicAdd(&(bar)[XB_TMO], 1u); break; } } } } while (0)
; __device__ __forceinline__ void xcd_barrier(const XcdBarrier& b) {
;     ...
;             else XB_SPIN(xb_ld(&bar[XB_TOPGEN]) == tg, bar);
;             __builtin_amdgcn_fence(__ATOMIC_ACQUIRE, "agent");
;             xb_add(&bar[XB_XGEN(b.x)], 1u);
;             asm volatile("s_waitcnt vmcnt(0)" ::: "memory");
;         } else {
;             XB_SPIN(xb_ld(&bar[XB_XGEN(b.x)]) == gen, bar);
;             __builtin_amdgcn_fence(__ATOMIC_ACQUIRE, "agent");
;             asm volatile("s_waitcnt vmcnt(0)" ::: "memory");
;         }
;     }
;     __syncthreads();
; }
; __device__ __forceinline__ void post_phase(const Params& p, int l, LAS unsigned char* lds, int tid) {
;     ...
;     for (int i = tid; i < 2048; i += NTHREADS) ropeL[i] = ((const float*)(ws + WS_ROPE))[i];
;     __syncthreads();
.Lxb_done_1:
	s_waitcnt vmcnt(0)
.LBB0_334:
	s_or_b64 exec, exec, s[0:1]
	s_movk_i32 s0, 0x800
	s_mov_b32 s83, s77
	s_waitcnt lgkmcnt(0)
	s_barrier
	s_nop 0
	v_cmp_gt_i32_e32 vcc, s0, v144
	s_and_saveexec_b64 s[0:1], vcc
	s_cbranch_execz .LBB0_347
	v_max_i32_e32 v0, 0x600, v144
	v_sub_u32_e32 v0, v0, v144
	v_add_u32_e32 v1, 0x1ff, v0
	s_movk_i32 s4, 0x1ff
	v_cmp_lt_u32_e32 vcc, s4, v1
	s_mov_b64 s[6:7], -1
	v_mov_b32_e32 v0, v144
	s_and_saveexec_b64 s[4:5], vcc
	s_cbranch_execz .LBB0_344
	v_lshrrev_b32_e32 v2, 9, v1
	v_add_u32_e32 v0, -1, v2
	v_add_u32_e32 v145, 0x200, v144
	v_lshrrev_b32_e32 v1, 1, v0
	v_add_u32_e32 v3, 1, v1
	v_cmp_lt_u32_e32 vcc, 13, v0
	v_mov_b32_e32 v6, 0
	v_mov_b64_e32 v[0:1], v[144:145]
	s_and_saveexec_b64 s[6:7], vcc
	s_cbranch_execz .LBB0_340
	v_readlane_b32 s8, v253, 12
	v_and_b32_e32 v4, -8, v3
	s_mov_b32 s10, 0
	v_lshl_add_u32 v5, v144, 2, s8
	s_mov_b64 s[8:9], 0
	v_mov_b64_e32 v[0:1], v[144:145]

; __device__ __forceinline__ unsigned xb_add(unsigned* p, unsigned v) { return __hip_atomic_fetch_add(p, v, __ATOMIC_RELAXED, __HIP_MEMORY_SCOPE_AGENT); }
; __device__ __forceinline__ void xcd_barrier(const XcdBarrier& b) {
;     asm volatile("s_waitcnt vmcnt(0)" ::: "memory");
;     __syncthreads();
;     if (threadIdx.x == 0) {
;         unsigned* bar = b.bar;
;         __builtin_amdgcn_s_waitcnt(0);
;         unsigned nloc = b.st[0], nx = b.st[1];
;         if (nloc == 0u) { xcd_barrier_complete(bar, b.x, nloc, nx); b.st[0] = nloc; b.st[1] = nx; }
;         const unsigned old = xb_add(&bar[XB_XSUB(b.x)], 1u);
.LBB0_400:
	s_waitcnt vmcnt(0) lgkmcnt(0)
	s_barrier
	s_add_i32 s98, s98, 1
	s_mov_b64 s[0:1], exec
	v_readlane_b32 s6, v252, 0
	v_readlane_b32 s7, v252, 1
	s_and_b64 s[6:7], s[0:1], s[6:7]
	v_readlane_b32 s12, v253, 29
	v_readlane_b32 s28, v253, 31
	v_readlane_b32 s13, v253, 30
	v_readlane_b32 s29, v253, 32
	s_mov_b64 exec, s[6:7]
	s_cbranch_execz .LBB0_452
	s_add_u32 s10, s88, 0x9000
	s_addc_u32 s11, s89, 0
	s_cmp_lg_u32 s100, 0
	s_cbranch_scc1 .Lxb_have_2
	s_add_u32 s8, s88, 0x1400
	s_addc_u32 s9, s89, 0

; #define LAS __attribute__((address_space(3)))
; #define GAS __attribute__((address_space(1)))
; __device__ __forceinline__ unsigned xb_ld(unsigned* p)              { return __hip_atomic_load(p, __ATOMIC_RELAXED, __HIP_MEMORY_SCOPE_AGENT); }
; __device__ __forceinline__ void xcd_barrier(const XcdBarrier& b) {
;     ...
;             else XB_SPIN(xb_ld(&bar[XB_TOPGEN]) == tg, bar);
;             __builtin_amdgcn_fence(__ATOMIC_ACQUIRE, "agent");
;             xb_add(&bar[XB_XGEN(b.x)], 1u);
;             asm volatile("s_waitcnt vmcnt(0)" ::: "memory");
;         } else {
;             XB_SPIN(xb_ld(&bar[XB_XGEN(b.x)]) == gen, bar);
;             __builtin_amdgcn_fence(__ATOMIC_ACQUIRE, "agent");
;             asm volatile("s_waitcnt vmcnt(0)" ::: "memory");
;         }
;     }
;     __syncthreads();
; }
; __device__ __forceinline__ void fft_phase(const Params& p, LAS unsigned char* lds, int tid) {
;     ...
;     LAS unsigned short* Z = (LAS unsigned short*)lds;
;     const int lane = tid & 63, w = tid >> 6, r32 = lane & 31, hi = lane >> 5;
;     for (int u = blockIdx.x; u < 256; u += gridDim.x) {
;         const int b = u >> 5, g = (u >> 3) & 3, cb = u & 7;
;         {
;             u32x4 v[16];
; #pragma unroll
;             for (int j = 0; j < 16; ++j) v[j] = *(const u32x4*)(ZT + ((size_t)((j >> 3) * 2048 + b * 256 + g * 64 + cb * 8 + (j & 7))) * 4096 + tid * 8);
; #pragma unroll
;             for (int j = 0; j < 16; ++j) *(LAS u32x4*)(Z + j * 4096 + tid * 8) = v[j];
;         }
;         __syncthreads();
;         LAS unsigned short* Zr = Z + w * 4096; LAS unsigned short* Zi = Z + (8 + w) * 4096;
;         for (int nh = 0; nh < 2; ++nh) {
;             const int n2 = nh * 32 + r32;
;             int two = (n2 * 64 + 4 * hi) * 2; asm volatile("" : "+v"(two));
;             const GAS float* twp = (const GAS float*)TW + two;
;             f32x4 tw0[2][4], tw1[2][4];
; #pragma unroll
;             for (int rg = 0; rg < 4; ++rg) { tw0[0][rg] = *(const GAS f32x4*)(twp + (8 * rg) * 2); tw1[0][rg] = *(const GAS f32x4*)(twp + (8 * rg) * 2 + 4); }
;             bf16x8 bfA[8];
; #pragma unroll
;             for (int s = 0; s < 8; ++s) {
;                 const LAS unsigned short* q = Z + ((s >> 2) * 8 + w) * 4096 + (16 * (s & 3) + 8 * hi) * 64 + n2;
.Lxb_done_2:
	s_waitcnt vmcnt(0)
.LBB0_452:
	s_or_b64 exec, exec, s[0:1]
	v_readlane_b32 s0, v254, 56
	v_readlane_b32 s1, v254, 57
	s_andn2_b64 vcc, exec, s[0:1]
	s_waitcnt lgkmcnt(0)
	s_barrier
	s_cbranch_vccnz .LBB0_455
	v_lshlrev_b32_e32 v0, 3, v144
	v_readlane_b32 s0, v254, 50
	v_ashrrev_i32_e32 v5, 6, v144
	v_ashrrev_i32_e32 v1, 31, v0
	v_readlane_b32 s1, v254, 51
	v_bfe_u32 v3, v144, 5, 1
	v_and_b32_e32 v4, 31, v144
	v_lshl_add_u64 v[124:125], v[0:1], 1, s[0:1]
	v_lshl_add_u32 v0, v5, 13, 0
	v_add_u32_e32 v1, 0x10000, v0
	v_lshlrev_b32_e32 v6, 8, v3
	v_lshlrev_b32_e32 v8, 10, v3
	v_lshlrev_b32_e32 v12, 1, v4
	v_add3_u32 v130, v0, v8, v12
	v_add3_u32 v131, v1, v8, v12
	v_or_b32_e32 v8, v6, v4
	v_lshlrev_b32_e32 v8, 1, v8
	v_add_u32_e32 v132, v0, v8
	v_add_u32_e32 v133, v1, v8
	v_or_b32_e32 v8, 64, v6
	v_bitop3_b32 v12, v144, 8, 31 bitop3:0x6c
	v_or_b32_e32 v13, v8, v12
	v_bitop3_b32 v14, v6, v4, 8 bitop3:0xf6
	v_lshl_add_u32 v134, v14, 1, v0
	v_lshl_add_u32 v135, v13, 1, v1
	v_or_b32_e32 v13, 0x80, v6
	v_bitop3_b32 v14, v144, 16, 31 bitop3:0x6c
	v_or_b32_e32 v15, v13, v14
	v_bitop3_b32 v16, v6, v4, 16 bitop3:0xf6
	v_lshl_add_u32 v136, v16, 1, v0
	v_lshl_add_u32 v137, v15, 1, v1
	v_or_b32_e32 v15, 0xc0, v6
	v_bitop3_b32 v16, v144, 24, 31 bitop3:0x6c
	v_or_b32_e32 v17, v15, v16
	v_bitop3_b32 v18, v6, v4, 24 bitop3:0xf6
	v_lshl_add_u32 v139, v17, 1, v1
	v_or_b32_e32 v17, 0x200, v6
	v_lshl_add_u32 v138, v18, 1, v0
	v_or_b32_e32 v18, v17, v4
	v_lshl_add_u32 v140, v18, 1, v1
	v_or_b32_e32 v18, 0x240, v6
	v_or_b32_e32 v19, v18, v12
	v_lshl_add_u32 v141, v19, 1, v1
	v_or_b32_e32 v19, 0x280, v6
	v_or_b32_e32 v20, v19, v14
	v_lshl_add_u32 v142, v20, 1, v1
	v_or_b32_e32 v20, 0x2c0, v6
	v_or_b32_e32 v21, v20, v16
	v_lshl_add_u32 v143, v21, 1, v1
	v_or_b32_e32 v21, 0x400, v6
	v_or_b32_e32 v22, v21, v4
	v_lshl_add_u32 v145, v22, 1, v1
	v_or_b32_e32 v22, 0x440, v6
	v_or_b32_e32 v23, v22, v12
	v_lshl_add_u32 v146, v23, 1, v1
	v_or_b32_e32 v23, 0x480, v6
	v_or_b32_e32 v24, v23, v14
	v_lshl_add_u32 v147, v24, 1, v1
	v_or_b32_e32 v24, 0x4c0, v6
	v_or_b32_e32 v25, v24, v16
	v_lshl_add_u32 v148, v25, 1, v1
	v_or_b32_e32 v25, 0x600, v6
	v_or_b32_e32 v26, v25, v4
	v_lshl_add_u32 v149, v26, 1, v1
	v_or_b32_e32 v26, 0x640, v6
	v_or_b32_e32 v27, v26, v12
	v_lshl_add_u32 v150, v27, 1, v1
	v_or_b32_e32 v27, 0x680, v6
	v_or_b32_e32 v28, v27, v14
	v_lshl_add_u32 v151, v28, 1, v1
	v_or_b32_e32 v28, 0x6c0, v6
	v_or_b32_e32 v29, v28, v16
	v_lshl_add_u32 v152, v29, 1, v1
	v_or_b32_e32 v29, 0x800, v6
	v_or_b32_e32 v30, v29, v4
	v_lshl_add_u32 v153, v30, 1, v1
	v_or_b32_e32 v30, 0x840, v6
	v_or_b32_e32 v31, v30, v12
	v_lshl_add_u32 v154, v31, 1, v1
	v_or_b32_e32 v31, 0x880, v6
	v_or_b32_e32 v32, v31, v14
	v_lshl_add_u32 v155, v32, 1, v1
	v_or_b32_e32 v32, 0x8c0, v6
	v_or_b32_e32 v33, v32, v16
	v_lshl_add_u32 v156, v33, 1, v1
	v_or_b32_e32 v33, 0xa00, v6
	v_or_b32_e32 v34, v33, v4
	v_lshl_add_u32 v157, v34, 1, v1
	v_or_b32_e32 v34, 0xa40, v6
	v_or_b32_e32 v35, v34, v12
	v_lshl_add_u32 v158, v35, 1, v1
	v_or_b32_e32 v35, 0xa80, v6
	v_or_b32_e32 v36, v35, v14
	v_lshl_add_u32 v159, v36, 1, v1
	v_or_b32_e32 v36, 0xac0, v6
	v_or_b32_e32 v37, v36, v16
	v_lshl_add_u32 v160, v37, 1, v1
	v_or_b32_e32 v37, 0xc00, v6
	v_or_b32_e32 v38, v37, v4
	v_lshl_add_u32 v161, v38, 1, v1
	v_or_b32_e32 v38, 0xc40, v6
	v_or_b32_e32 v39, v38, v12
	v_lshl_add_u32 v162, v39, 1, v1
	v_or_b32_e32 v39, 0xc80, v6
	v_or_b32_e32 v40, v39, v14
	v_lshl_add_u32 v163, v40, 1, v1
	v_or_b32_e32 v40, 0xcc0, v6
	v_or_b32_e32 v41, v40, v16
	v_lshl_add_u32 v164, v41, 1, v1
	v_or_b32_e32 v41, 0xe00, v6
	v_or_b32_e32 v42, v41, v4
	v_lshl_add_u32 v165, v42, 1, v1
	v_or_b32_e32 v42, 0xe40, v6
	v_or_b32_e32 v12, v42, v12
	v_lshl_add_u32 v166, v12, 1, v1
	v_or_b32_e32 v12, 0xe80, v6
	v_or_b32_e32 v14, v12, v14
	v_lshl_add_u32 v167, v14, 1, v1
	v_or_b32_e32 v14, 0xec0, v6
; __device__ __forceinline__ void fft_phase(const Params& p, LAS unsigned char* lds, int tid) {
;     ...
;     const int lane = tid & 63, w = tid >> 6, r32 = lane & 31, hi = lane >> 5;
;     for (int u = blockIdx.x; u < 256; u += gridDim.x) {
;         const int b = u >> 5, g = (u >> 3) & 3, cb = u & 7;
;         {
;             u32x4 v[16];
; #pragma unroll
;             for (int j = 0; j < 16; ++j) v[j] = *(const u32x4*)(ZT + ((size_t)((j >> 3) * 2048 + b * 256 + g * 64 + cb * 8 + (j & 7))) * 4096 + tid * 8);
; #pragma unroll
;             for (int j = 0; j < 16; ++j) *(LAS u32x4*)(Z + j * 4096 + tid * 8) = v[j];
;         }
;         __syncthreads();
;         LAS unsigned short* Zr = Z + w * 4096; LAS unsigned short* Zi = Z + (8 + w) * 4096;
;         for (int nh = 0; nh < 2; ++nh) {
;             const int n2 = nh * 32 + r32;
;             int two = (n2 * 64 + 4 * hi) * 2; asm volatile("" : "+v"(two));
;             const GAS float* twp = (const GAS float*)TW + two;
;             f32x4 tw0[2][4], tw1[2][4];
; #pragma unroll
;             for (int rg = 0; rg < 4; ++rg) { tw0[0][rg] = *(const GAS f32x4*)(twp + (8 * rg) * 2); tw1[0][rg] = *(const GAS f32x4*)(twp + (8 * rg) * 2 + 4); }
;             bf16x8 bfA[8];
; #pragma unroll
;             for (int s = 0; s < 8; ++s) {
;                 const LAS unsigned short* q = Z + ((s >> 2) * 8 + w) * 4096 + (16 * (s & 3) + 8 * hi) * 64 + n2;
;                 u32x4 t;
;                 t.x = (unsigned)q[0] | ((unsigned)q[64] << 16); t.y = (unsigned)q[128] | ((unsigned)q[192] << 16);
;                 t.z = (unsigned)q[256] | ((unsigned)q[320] << 16); t.w = (unsigned)q[384] | ((unsigned)q[448] << 16);
;                 bfA[s] = __builtin_bit_cast(bf16x8, t);
;             }
;             f32x16 acc[4];
;             int fao = r32 * 128 + 8 * hi; asm volatile("" : "+v"(fao));
;             const GAS bf16_t* fap = (const GAS bf16_t*)FA + fao;
; #pragma unroll
;             for (int mt = 0; mt < 4; ++mt) {
; #pragma unroll
;                 for (int e = 0; e < 16; ++e) acc[mt][e] = 0.f;
; #pragma unroll
;                 for (int s = 0; s < 8; ++s) {
;                     const bf16x8 a = *(const GAS bf16x8*)(fap + mt * 32 * 128 + 16 * s);
;                     acc[mt] = __builtin_amdgcn_mfma_f32_32x32x16_bf16(a, bfA[s], acc[mt], 0, 0, 0);
;                 }
;                 asm volatile("" ::: "memory");
;             }
	v_or_b32_e32 v16, v14, v16
	v_lshlrev_b32_e32 v7, 3, v3
	v_lshlrev_b32_e32 v9, 7, v4
	v_lshl_add_u32 v168, v16, 1, v1
	v_or_b32_e32 v16, 32, v4
	v_or_b32_e32 v129, v7, v9
	v_and_b32_e32 v10, 7, v144
	v_lshl_or_b32 v169, v16, 7, v7
	v_bitop3_b32 v7, v4, 56, 32 bitop3:0xc8
	v_or_b32_e32 v16, v7, v10
	v_or_b32_e32 v43, v16, v6
	v_lshlrev_b32_e32 v43, 1, v43
	v_bitop3_b32 v44, v16, v6, 8 bitop3:0xde
	v_add_u32_e32 v170, v0, v43
	v_add_u32_e32 v171, v1, v43
	v_bitop3_b32 v43, v7, 8, v10 bitop3:0x36
	v_lshl_add_u32 v172, v44, 1, v0
	v_bitop3_b32 v44, v16, v6, 16 bitop3:0xde
	v_bitop3_b32 v6, v16, v6, 24 bitop3:0xde
	v_or_b32_e32 v8, v43, v8
	v_lshl_add_u32 v176, v6, 1, v0
	v_or_b32_e32 v6, v16, v17
	v_lshl_add_u32 v173, v8, 1, v1
	v_bitop3_b32 v8, v7, 16, v10 bitop3:0x36
	v_lshl_add_u32 v178, v6, 1, v1
	v_or_b32_e32 v6, v43, v18
	v_bitop3_b32 v7, v7, 24, v10 bitop3:0x36
	v_lshl_add_u32 v179, v6, 1, v1
	v_or_b32_e32 v6, v8, v19
	v_lshl_add_u32 v180, v6, 1, v1
	v_or_b32_e32 v6, v7, v20
	v_lshl_add_u32 v181, v6, 1, v1
	v_or_b32_e32 v6, v16, v21
	v_lshl_add_u32 v182, v6, 1, v1
	v_or_b32_e32 v6, v43, v22
	v_lshl_add_u32 v183, v6, 1, v1
	v_or_b32_e32 v6, v8, v23
	v_lshl_add_u32 v184, v6, 1, v1
	v_or_b32_e32 v6, v7, v24
	v_lshl_add_u32 v185, v6, 1, v1
	v_or_b32_e32 v6, v16, v25
	v_lshl_add_u32 v186, v6, 1, v1
	v_or_b32_e32 v6, v43, v26
	v_lshl_add_u32 v192, v6, 1, v1
	v_or_b32_e32 v6, v8, v27
	v_lshl_add_u32 v193, v6, 1, v1
	v_or_b32_e32 v6, v7, v28
	v_lshl_add_u32 v194, v6, 1, v1
	v_or_b32_e32 v6, v16, v29
	v_lshl_add_u32 v195, v6, 1, v1
	v_or_b32_e32 v6, v43, v30
	v_lshl_add_u32 v196, v6, 1, v1
	v_or_b32_e32 v6, v8, v31
	v_lshl_add_u32 v197, v6, 1, v1
	v_or_b32_e32 v6, v7, v32
	v_lshl_add_u32 v198, v6, 1, v1
	v_or_b32_e32 v6, v16, v33
	v_lshl_add_u32 v199, v6, 1, v1
	v_or_b32_e32 v6, v43, v34
	v_lshl_add_u32 v200, v6, 1, v1
	v_or_b32_e32 v6, v8, v35
	v_lshl_add_u32 v201, v6, 1, v1
	v_or_b32_e32 v6, v7, v36
	v_lshl_add_u32 v202, v6, 1, v1
	v_or_b32_e32 v6, v16, v37
	v_lshl_add_u32 v203, v6, 1, v1
	v_or_b32_e32 v6, v43, v38
	v_lshl_add_u32 v204, v6, 1, v1
	v_or_b32_e32 v6, v8, v39
	v_lshrrev_b32_e32 v2, 5, v144
	v_and_b32_e32 v11, 3, v144
	v_lshl_add_u32 v205, v6, 1, v1
	v_or_b32_e32 v6, v7, v40
	v_lshl_add_u32 v174, v44, 1, v0
	v_lshl_add_u32 v206, v6, 1, v1
	v_or_b32_e32 v6, v16, v41
	v_add_u32_e32 v211, v0, v9
	v_bitop3_b32 v0, v2, v11, 1 bitop3:0x6c
	v_lshl_add_u32 v207, v6, 1, v1
	v_or_b32_e32 v6, v43, v42
	v_lshlrev_b32_e32 v212, 4, v0
	v_bitop3_b32 v0, v3, v11, 2 bitop3:0x36
	v_lshl_add_u32 v208, v6, 1, v1
	v_or_b32_e32 v6, v8, v12
	v_lshlrev_b32_e32 v213, 4, v0
	v_bitop3_b32 v0, v3, v11, 4 bitop3:0x36
	v_or_b32_e32 v13, v8, v13
	v_or_b32_e32 v10, v7, v15
	v_lshl_add_u32 v209, v6, 1, v1
	v_or_b32_e32 v6, v7, v14
	v_lshlrev_b32_e32 v214, 4, v0
	v_bitop3_b32 v0, v3, v11, 6 bitop3:0x36
	v_lshl_add_u32 v5, v5, 1, 0
	v_lshl_add_u32 v175, v13, 1, v1
	v_lshl_add_u32 v177, v10, 1, v1
	v_lshl_add_u32 v210, v6, 1, v1
	v_lshlrev_b32_e32 v215, 4, v0
	v_lshlrev_b32_e32 v0, 12, v3
	v_lshlrev_b32_e32 v1, 4, v4
	v_add_u32_e32 v219, 0x200, v144
	v_add_u32_e32 v234, 0x400, v144
	v_add_u32_e32 v235, 0x600, v144
	v_add_u32_e32 v236, 0x800, v144
	v_add_u32_e32 v237, 0xa00, v144
	v_add_u32_e32 v238, 0xc00, v144
	v_add_u32_e32 v239, 0xe00, v144
	v_add3_u32 v218, v5, v0, v1
	v_lshlrev_b32_e32 v0, 4, v219
	v_lshlrev_b32_e32 v1, 4, v234
	v_lshlrev_b32_e32 v2, 4, v235
	v_lshlrev_b32_e32 v3, 4, v236
	v_lshlrev_b32_e32 v4, 4, v237
	v_lshlrev_b32_e32 v5, 4, v238
	v_lshlrev_b32_e32 v6, 4, v239
	v_lshl_add_u32 v128, v144, 4, 0
	v_add_u32_e32 v216, 0x10000, v211
	v_add_u32_e32 v217, 0x11000, v211
	v_add_u32_e32 v240, 0, v0
	v_add_u32_e32 v241, 0, v1
	v_add_u32_e32 v242, 0, v2
	v_add_u32_e32 v243, 0, v3
	v_add_u32_e32 v244, 0, v4
	v_add_u32_e32 v245, 0, v5
	v_add_u32_e32 v246, 0, v6
	v_readlane_b32 s4, v252, 29
	s_mov_b32 s5, s2

; __device__ __forceinline__ unsigned xb_ld(unsigned* p)              { return __hip_atomic_load(p, __ATOMIC_RELAXED, __HIP_MEMORY_SCOPE_AGENT); }
; __device__ __forceinline__ unsigned xb_add(unsigned* p, unsigned v) { return __hip_atomic_fetch_add(p, v, __ATOMIC_RELAXED, __HIP_MEMORY_SCOPE_AGENT); }
; #define XB_SPIN(cond, bar) do { unsigned _sp = 0; while (cond) { __builtin_amdgcn_s_sleep(1); \
;     if ((++_sp & 255u) == 0u) { if (xb_ld(&(bar)[XB_TMO])) break; if (_sp > XB_SPIN_CAP) { atomicAdd(&(bar)[XB_TMO], 1u); break; } } } } while (0)
;     __device__ bool next(int i, pg8::Unit& u) const { if (i != 0 || !has) return false; u.pm = pm; u.pn = pn; return true; }
;     __host__ __device__ bool next(int i, Unit& u) const {
;         const long L = (long)i * G + c; if (L >= nwg) return false;
;         int wgid = (int)L; { const int q = nwg / NXCD, r = nwg % NXCD, xcd = wgid % NXCD, off = wgid / NXCD; wgid = (xcd < r ? xcd * (q + 1) : r * (q + 1) + (xcd - r) * q) + off; }
;         const int nig = WGM * nN, gid = wgid / nig, fm = gid * WGM, gsz = (nM - fm) < WGM ? (nM - fm) : WGM;
;         u.pm = fm + ((wgid % nig) % gsz); u.pn = (wgid % nig) / gsz; return true;
;     }
; __device__ __forceinline__ void xcd_barrier(const XcdBarrier& b) {
;     ...
;             else XB_SPIN(xb_ld(&bar[XB_TOPGEN]) == tg, bar);
;             __builtin_amdgcn_fence(__ATOMIC_ACQUIRE, "agent");
;             xb_add(&bar[XB_XGEN(b.x)], 1u);
;             asm volatile("s_waitcnt vmcnt(0)" ::: "memory");
;         } else {
;             XB_SPIN(xb_ld(&bar[XB_XGEN(b.x)]) == gen, bar);
;             __builtin_amdgcn_fence(__ATOMIC_ACQUIRE, "agent");
;             asm volatile("s_waitcnt vmcnt(0)" ::: "memory");
;         }
;     }
;     __syncthreads();
; }
.Lxb_done_3:
	s_waitcnt vmcnt(0)
.LBB0_543:
	s_or_b64 exec, exec, s[0:1]
	s_and_b64 s[0:1], s[64:65], exec
	s_movk_i32 s0, 0x88
	s_cselect_b32 s28, s0, 0x80
	s_lshl_b32 s42, s28, 2
	s_cmp_lt_i32 s2, s42
	v_mov_b32_e32 v8, v220
	s_cselect_b64 s[0:1], -1, 0
	s_waitcnt lgkmcnt(0)
	s_barrier
	s_and_b64 vcc, exec, s[0:1]
	v_readfirstlane_b32 s4, v8
	s_cbranch_vccz .LBB0_545
	s_lshr_b32 s5, s28, 1
	v_readlane_b32 s6, v254, 62
	s_or_b32 s5, s5, s6
	v_readlane_b32 s6, v255, 30
	s_mul_i32 s5, s5, s6
	v_readlane_b32 s6, v255, 31
	s_add_i32 s5, s5, s6
	s_ashr_i32 s6, s5, 31
	s_lshr_b32 s6, s6, 27
	s_add_i32 s6, s5, s6
	s_ashr_i32 s7, s6, 5
	s_lshl_b32 s9, s7, 3
	s_sub_i32 s7, s28, s9
	s_min_i32 s10, s7, 8
	s_sext_i32_i8 s7, s10
	v_cvt_f32_i32_e32 v0, s7
	s_andn2_b32 s6, s6, 31
	s_sub_i32 s5, s5, s6
	v_cvt_f32_i32_e32 v1, s5
	v_rcp_iflag_f32_e32 v2, v0
	s_xor_b32 s6, s5, s7
	s_ashr_i32 s6, s6, 30
	s_or_b32 s8, s6, 1
	v_mul_f32_e32 v2, v1, v2
	v_trunc_f32_e32 v2, v2
	v_fma_f32 v1, -v2, v0, v1
	v_cvt_i32_f32_e32 v2, v2
	v_cmp_ge_f32_e64 s[6:7], |v1|, |v0|
	s_and_b64 s[6:7], s[6:7], exec
	s_cselect_b32 s6, s8, 0
	v_readfirstlane_b32 s7, v2
	s_add_i32 s6, s7, s6
	s_sext_i32_i8 s8, s6
	s_mul_i32 s6, s6, s10
	s_sub_i32 s5, s5, s6
	s_sext_i32_i8 s5, s5
	s_add_i32 s36, s9, s5

; #define PG8_WAIT_V(n) asm volatile("s_waitcnt vmcnt(" #n ")" ::: "memory")
; template <class Epi, class Sched, bool ALIGN_EPI = false, bool SP2 = false>
; __device__ __forceinline__ void gemm_phase(PG8_LAS unsigned char* lds, const Gemm g, const Sched& S, const Epi& E) {
;     int tid_ = threadIdx.x; asm volatile("" : "+v"(tid_)); const int tid = tid_, wid = __builtin_amdgcn_readfirstlane(tid >> 6), lane = tid & 63, wr = wid >> 2, wc = wid & 3, fr = lane & 15, fq = lane >> 4;
;     const int K = g.K, nt = K / BK, LD = g.ld ? g.ld : g.K;
;     unsigned voffA[2], voffB[2];
; #pragma unroll
;     for (int i = 0; i < 2; ++i) { int R, C; stage_rc(tid * 16 + i * 8192, R, C); const int Rb = Epi::PERM ? ((R & ~31) + perm32(R & 31)) : R;
;         voffA[i] = (unsigned)(R * LD + C) * 2u; voffB[i] = (unsigned)(Rb * LD + C) * 2u; }
;     const size_t kstep = (size_t)(BK * 2);
;     const size_t hstep = (size_t)HALF * LD * 2;
;     const size_t tstep = 2 * hstep;
;     const unsigned ldsw = (unsigned)wid * 1024u;
;     const int aoff = lds_byte(wr * 64 + fr, fq * 8), boff = lds_byte(wc * 32 + fr, fq * 8);
;     ...
;     Unit cur, nxt; int ui = 0;
;     if (!S.next(0, cur)) return;
;     f32x4 acc[2][2][4][2];
; #pragma unroll
;     for (int a = 0; a < 2; ++a)
; #pragma unroll
;         for (int b = 0; b < 2; ++b)
; #pragma unroll
;             for (int m = 0; m < 4; ++m)
; #pragma unroll
;                 for (int n = 0; n < 2; ++n) acc[a][b][m][n] = (f32x4){0.f, 0.f, 0.f, 0.f};
;     bf16x8 At[4][2], B0[2][2], B1[2][2];
;     const char* cA = (const char*)g.A + (size_t)cur.pm * tstep; const char* cB = (const char*)g.Bt + (size_t)cur.pn * tstep;
;     S.a_ready(cur);
;     if constexpr (SP2) {
;         PG8_STAGE(PG8_SB(0, 0), cB, voffB); PG8_STAGE(PG8_SB(0, 1), cB + hstep, voffB); PG8_STAGE(PG8_SA(0, 0), cA, voffA); PG8_STAGE(PG8_SA(0, 1), cA + hstep, voffA);
;         if (wr == 1) PG8_BAR;
;         PG8_WAIT_V(2); PG8_BAR;
;         PG8_STAGE(PG8_SB(1, 0), cB + kstep, voffB); PG8_STAGE(PG8_SA(1, 0), cA + kstep, voffA); PG8_STAGE(PG8_SB(1, 1), cB + hstep + kstep, voffB);
;         PG8_WAIT_V(6); PG8_BAR;
;     } else {
;         PG8_STAGE(PG8_SB(0, 0), cB, voffB); PG8_STAGE(PG8_SA(0, 0), cA, voffA); PG8_STAGE(PG8_SB(0, 1), cB + hstep, voffB); PG8_STAGE(PG8_SA(0, 1), cA + hstep, voffA);
;         if (wr == 1) PG8_BAR;
;         PG8_WAIT_V(4); PG8_BAR;
.Lxb_done_4:
	s_waitcnt vmcnt(0)
.LBB0_629:
	s_or_b64 exec, exec, s[0:1]
	s_lshl_b64 s[4:5], s[82:83], 23
	s_lshl_b32 s76, s28, 4
	v_mov_b32_e32 v14, v220
	s_waitcnt lgkmcnt(0)
	s_barrier
	s_cmp_lt_i32 s2, s76
	v_readfirstlane_b32 s0, v14
	s_cbranch_scc0 .LBB0_645
	v_lshlrev_b32_e32 v0, 4, v14
	v_add_u32_e32 v1, 0x2000, v0
	v_ashrrev_i32_e32 v2, 31, v1
	v_lshrrev_b32_e32 v2, 22, v2
	v_add_u32_e32 v2, v1, v2
	v_ashrrev_i32_e32 v8, 10, v2
	v_mul_i32_i24_e32 v2, 0x400, v8
	v_sub_u32_e32 v1, v1, v2
	v_lshrrev_b32_e32 v2, 4, v1
	v_bitop3_b32 v1, v2, v1, 32 bitop3:0x6c
	v_ashrrev_i32_e32 v2, 31, v1
	v_lshrrev_b32_e32 v2, 26, v2
	v_add_u32_e32 v2, v1, v2
	v_lshlrev_b32_e32 v3, 3, v8
	v_ashrrev_i32_e32 v9, 6, v2
	v_and_b32_e32 v3, -16, v3
	v_add_u32_e32 v3, v9, v3
	v_and_b32_e32 v4, 3, v9
	s_mov_b32 s7, 0x1fffe0
	v_lshrrev_b32_e32 v5, 2, v3
	v_lshlrev_b32_e32 v6, 1, v3
	v_and_b32_e32 v2, 0xc0, v2
	v_and_or_b32 v4, v3, s7, v4
	v_and_b32_e32 v5, 4, v5
	v_and_b32_e32 v6, 24, v6
	v_sub_u32_e32 v1, v1, v2
	v_or3_b32 v4, v4, v5, v6
	v_lshlrev_b32_e32 v5, 5, v8
	v_ashrrev_i16_sdwa v1, v222, sext(v1) dst_sel:DWORD dst_unused:UNUSED_PAD src0_sel:DWORD src1_sel:BYTE_0
	v_and_b32_e32 v5, 32, v5
	v_bfe_i32 v10, v1, 0, 16
	v_add_lshl_u32 v1, v5, v10, 1
	v_lshl_add_u32 v146, v4, 11, v1
	v_lshl_add_u32 v148, v3, 11, v1
	v_bfe_i32 v1, v14, 27, 1
	v_lshrrev_b32_e32 v1, 22, v1
	v_add_u32_e32 v1, v0, v1
	v_and_b32_e32 v1, 0xfffffc00, v1
	v_sub_u32_e32 v0, v0, v1
	v_lshrrev_b32_e32 v1, 4, v0
	v_ashrrev_i32_e32 v2, 31, v14
	v_bitop3_b32 v0, v1, v0, 32 bitop3:0x6c
	v_lshrrev_b32_e32 v2, 26, v2
	v_readlane_b32 s1, v253, 35
	v_ashrrev_i32_e32 v1, 31, v0
	v_add_u32_e32 v2, v14, v2
	s_add_u32 s31, s1, s4
	v_readlane_b32 s1, v253, 36
	v_lshrrev_b32_e32 v1, 26, v1
	v_ashrrev_i32_e32 v12, 6, v2
	s_addc_u32 s34, s1, s5
	s_ashr_i32 s1, s0, 6
	v_add_u32_e32 v1, v0, v1
	v_lshlrev_b32_e32 v2, 3, v12
	s_lshl_b32 s43, s28, 1
	v_readlane_b32 s8, v255, 17
	s_ashr_i32 s6, s0, 8
	s_lshl_b32 s35, s1, 10
	v_ashrrev_i32_e32 v11, 6, v1
	v_and_b32_e32 v2, -16, v2
	s_or_b32 s52, s43, 1
	v_readlane_b32 s9, v255, 18
	v_add_u32_e32 v2, v11, v2
	v_and_b32_e32 v3, 3, v11
	s_and_b64 s[8:9], s[8:9], exec
	v_and_or_b32 v3, v2, s7, v3
	s_cselect_b32 s7, s52, s43
	v_readlane_b32 s8, v255, 30
	s_mul_i32 s7, s7, s8
	v_readlane_b32 s8, v255, 31
	s_add_i32 s7, s7, s8
	s_ashr_i32 s8, s7, 31
	s_lshr_b32 s8, s8, 25
	s_add_i32 s8, s7, s8
	s_ashr_i32 s9, s8, 7
	s_lshl_b32 s9, s9, 3
	v_and_b32_e32 v1, 0xc0, v1
	s_sub_i32 s10, s28, s9
	v_sub_u32_e32 v0, v0, v1
	s_min_i32 s11, s10, 8
	v_ashrrev_i16_sdwa v0, v222, sext(v0) dst_sel:DWORD dst_unused:UNUSED_PAD src0_sel:DWORD src1_sel:BYTE_0
	s_abs_i32 s10, s11
	v_bfe_i32 v13, v0, 0, 16
	v_cvt_f32_u32_e32 v0, s10
	s_sub_i32 s13, 0, s10
	s_and_b32 s8, s8, 0xffffff80
	s_sub_i32 s7, s7, s8
	v_rcp_iflag_f32_e32 v0, v0
	s_abs_i32 s12, s7
	s_xor_b32 s8, s7, s11
	s_ashr_i32 s8, s8, 31
	v_mul_f32_e32 v0, 0x4f7ffffe, v0
	v_cvt_u32_f32_e32 v0, v0
	v_lshrrev_b32_e32 v4, 2, v2
	v_lshlrev_b32_e32 v5, 1, v2
	v_and_b32_e32 v4, 4, v4
	v_readfirstlane_b32 s36, v0
	s_mul_i32 s13, s13, s36
	s_mul_hi_u32 s13, s36, s13
	s_add_i32 s36, s36, s13
	s_mul_hi_u32 s13, s12, s36
	s_mul_i32 s36, s13, s10
	s_sub_i32 s12, s12, s36
	s_add_i32 s36, s13, 1
	s_sub_i32 s37, s12, s10
	s_cmp_ge_u32 s12, s10
	s_cselect_b32 s13, s36, s13
	s_cselect_b32 s12, s37, s12
	s_add_i32 s36, s13, 1
	s_cmp_ge_u32 s12, s10
	s_cselect_b32 s10, s36, s13
	s_xor_b32 s10, s10, s8
	s_sub_i32 s10, s10, s8
	s_mul_i32 s8, s10, s11
	s_sub_i32 s7, s7, s8
	s_add_i32 s48, s9, s7
	v_and_b32_e32 v5, 24, v5
	s_ashr_i32 s49, s48, 31
	s_ashr_i32 s11, s10, 31
	v_or3_b32 v3, v3, v4, v5
	v_lshlrev_b32_e32 v4, 5, v12
	s_lshl_b64 s[8:9], s[48:49], 19
	s_lshl_b64 s[12:13], s[10:11], 19
	v_and_b32_e32 v4, 32, v4
	s_add_u32 s12, s31, s12
	v_add_lshl_u32 v1, v4, v13, 1
	s_addc_u32 s13, s34, s13
	s_add_i32 s49, s35, 0
	v_lshl_add_u32 v150, v3, 11, v1
	s_add_i32 m0, s49, 0x10000
	v_lshl_add_u32 v152, v2, 11, v1
	global_load_lds_dwordx4 v150, s[12:13]
	s_add_i32 m0, s49, 0x12000
	s_add_u32 s36, s12, 0x40000
	global_load_lds_dwordx4 v146, s[12:13]
	s_addc_u32 s37, s13, 0
	s_add_i32 m0, s49, 0x14000
	v_mov_b32_e32 v151, v187
	global_load_lds_dwordx4 v150, s[36:37]
	s_add_i32 m0, s49, 0x16000
	v_mov_b32_e32 v147, v187
	global_load_lds_dwordx4 v146, s[36:37]
	v_readlane_b32 s36, v255, 24
	v_readlane_b32 s37, v255, 25
	s_add_u32 s54, s36, s8
	s_addc_u32 s55, s37, s9
	s_add_i32 s53, s49, 0x2000
	s_mov_b32 m0, s49
	s_add_u32 s8, s54, 0x40000
	global_load_lds_dwordx4 v152, s[54:55]
	s_mov_b32 m0, s53
	s_addc_u32 s9, s55, 0
	s_add_i32 s56, s49, 0x4000
	global_load_lds_dwordx4 v148, s[54:55]
	s_mov_b32 m0, s56
	s_add_i32 s57, s49, 0x6000
	global_load_lds_dwordx4 v152, s[8:9]
	s_mov_b32 m0, s57
	v_mov_b32_e32 v153, v187
	global_load_lds_dwordx4 v148, s[8:9]
	v_mov_b32_e32 v149, v187
	s_cmp_eq_u32 s6, 1
	v_lshl_add_u64 v[6:7], s[12:13], 0, v[150:151]
	v_lshl_add_u64 v[4:5], s[12:13], 0, v[146:147]
	v_lshl_add_u64 v[0:1], s[54:55], 0, v[152:153]
	s_cselect_b64 s[38:39], -1, 0
	s_cmp_lg_u32 s6, 1
	v_lshl_add_u64 v[2:3], s[54:55], 0, v[148:149]
	s_cbranch_scc1 .LBB0_632
	s_barrier

; #define PG8_WAIT_V(n) asm volatile("s_waitcnt vmcnt(" #n ")" ::: "memory")
; template <class Epi, class Sched, bool ALIGN_EPI = false, bool SP2 = false>
; __device__ __forceinline__ void gemm_phase(PG8_LAS unsigned char* lds, const Gemm g, const Sched& S, const Epi& E) {
;     int tid_ = threadIdx.x; asm volatile("" : "+v"(tid_)); const int tid = tid_, wid = __builtin_amdgcn_readfirstlane(tid >> 6), lane = tid & 63, wr = wid >> 2, wc = wid & 3, fr = lane & 15, fq = lane >> 4;
;     const int K = g.K, nt = K / BK, LD = g.ld ? g.ld : g.K;
;     unsigned voffA[2], voffB[2];
; #pragma unroll
;     for (int i = 0; i < 2; ++i) { int R, C; stage_rc(tid * 16 + i * 8192, R, C); const int Rb = Epi::PERM ? ((R & ~31) + perm32(R & 31)) : R;
;         voffA[i] = (unsigned)(R * LD + C) * 2u; voffB[i] = (unsigned)(Rb * LD + C) * 2u; }
;     const size_t kstep = (size_t)(BK * 2);
;     const size_t hstep = (size_t)HALF * LD * 2;
;     const size_t tstep = 2 * hstep;
;     const unsigned ldsw = (unsigned)wid * 1024u;
;     const int aoff = lds_byte(wr * 64 + fr, fq * 8), boff = lds_byte(wc * 32 + fr, fq * 8);
;     ...
;     Unit cur, nxt; int ui = 0;
;     if (!S.next(0, cur)) return;
;     f32x4 acc[2][2][4][2];
; #pragma unroll
;     for (int a = 0; a < 2; ++a)
; #pragma unroll
;         for (int b = 0; b < 2; ++b)
; #pragma unroll
;             for (int m = 0; m < 4; ++m)
; #pragma unroll
;                 for (int n = 0; n < 2; ++n) acc[a][b][m][n] = (f32x4){0.f, 0.f, 0.f, 0.f};
;     bf16x8 At[4][2], B0[2][2], B1[2][2];
;     const char* cA = (const char*)g.A + (size_t)cur.pm * tstep; const char* cB = (const char*)g.Bt + (size_t)cur.pn * tstep;
;     S.a_ready(cur);
;     if constexpr (SP2) {
;         PG8_STAGE(PG8_SB(0, 0), cB, voffB); PG8_STAGE(PG8_SB(0, 1), cB + hstep, voffB); PG8_STAGE(PG8_SA(0, 0), cA, voffA); PG8_STAGE(PG8_SA(0, 1), cA + hstep, voffA);
;         if (wr == 1) PG8_BAR;
;         PG8_WAIT_V(2); PG8_BAR;
;         PG8_STAGE(PG8_SB(1, 0), cB + kstep, voffB); PG8_STAGE(PG8_SA(1, 0), cA + kstep, voffA); PG8_STAGE(PG8_SB(1, 1), cB + hstep + kstep, voffB);
;         PG8_WAIT_V(6); PG8_BAR;
;     } else {
;         PG8_STAGE(PG8_SB(0, 0), cB, voffB); PG8_STAGE(PG8_SA(0, 0), cA, voffA); PG8_STAGE(PG8_SB(0, 1), cB + hstep, voffB); PG8_STAGE(PG8_SA(0, 1), cA + hstep, voffA);
;         if (wr == 1) PG8_BAR;
;         PG8_WAIT_V(4); PG8_BAR;
.Lxb_done_5:
	s_waitcnt vmcnt(0)
.LBB0_697:
	s_or_b64 exec, exec, s[0:1]
	s_add_u32 s29, s59, s4
	v_readlane_b32 s0, v253, 34
	s_addc_u32 s30, s0, s5
	v_readlane_b32 s0, v253, 41
	v_readlane_b32 s4, v253, 49
	v_readlane_b32 s1, v253, 42
	s_add_u32 s31, s0, 0x5000
	v_readlane_b32 s5, v253, 50
	s_addc_u32 s92, s1, 0
	s_mov_b64 s[0:1], -1
	s_and_b64 vcc, exec, s[4:5]
	v_readlane_b32 s76, v255, 9
	v_readlane_b32 s82, v255, 10
	v_readlane_b32 s83, v253, 6
	v_readlane_b32 s93, v253, 7
	s_waitcnt lgkmcnt(0)
	s_barrier
	s_cbranch_vccz .LBB0_715
	v_readlane_b32 s0, v253, 51
	v_mov_b32_e32 v10, v220
	v_readlane_b32 s1, v253, 52
	s_and_b64 vcc, exec, s[0:1]
	v_readfirstlane_b32 s1, v10
	s_cbranch_vccnz .LBB0_714
	v_lshlrev_b32_e32 v0, 4, v10
	v_add_u32_e32 v1, 0x2000, v0
	v_ashrrev_i32_e32 v2, 31, v1
	v_lshrrev_b32_e32 v2, 22, v2
	v_add_u32_e32 v2, v1, v2
	v_ashrrev_i32_e32 v4, 10, v2
	v_mul_i32_i24_e32 v2, 0x400, v4
	v_sub_u32_e32 v1, v1, v2
	v_lshrrev_b32_e32 v2, 4, v1
	v_bitop3_b32 v1, v2, v1, 32 bitop3:0x6c
	v_ashrrev_i32_e32 v2, 31, v1
	v_lshrrev_b32_e32 v2, 26, v2
	v_add_u32_e32 v2, v1, v2
	v_lshlrev_b32_e32 v3, 3, v4
	v_ashrrev_i32_e32 v5, 6, v2
	v_and_b32_e32 v3, -16, v3
	v_add_u32_e32 v3, v5, v3
	v_and_b32_e32 v6, 3, v5
	s_mov_b32 s4, 0x7ffe0
	v_lshrrev_b32_e32 v7, 2, v3
	v_lshlrev_b32_e32 v8, 1, v3
	v_and_b32_e32 v2, 0xc0, v2
	v_and_or_b32 v6, v3, s4, v6
	v_and_b32_e32 v7, 4, v7
	v_and_b32_e32 v8, 24, v8
	v_sub_u32_e32 v1, v1, v2
	v_or3_b32 v7, v6, v7, v8
	v_lshlrev_b32_e32 v6, 5, v4
	v_ashrrev_i16_sdwa v1, v222, sext(v1) dst_sel:DWORD dst_unused:UNUSED_PAD src0_sel:DWORD src1_sel:BYTE_0
	v_and_b32_e32 v8, 32, v6
	v_bfe_i32 v6, v1, 0, 16
	v_add_lshl_u32 v1, v8, v6, 1
	v_lshl_add_u32 v146, v7, 13, v1
	v_lshl_add_u32 v148, v3, 13, v1
	v_bfe_i32 v1, v10, 27, 1
	v_lshrrev_b32_e32 v1, 22, v1
	v_add_u32_e32 v1, v0, v1
	v_and_b32_e32 v1, 0xfffffc00, v1
	v_sub_u32_e32 v0, v0, v1
	v_lshrrev_b32_e32 v1, 4, v0
	v_ashrrev_i32_e32 v2, 31, v10
	v_bitop3_b32 v0, v1, v0, 32 bitop3:0x6c
	v_lshrrev_b32_e32 v2, 26, v2
	v_ashrrev_i32_e32 v1, 31, v0
	v_add_u32_e32 v2, v10, v2
	v_lshrrev_b32_e32 v1, 26, v1
	v_ashrrev_i32_e32 v8, 6, v2
	v_add_u32_e32 v1, v0, v1
	v_lshlrev_b32_e32 v2, 3, v8
	v_ashrrev_i32_e32 v7, 6, v1
	v_and_b32_e32 v2, -16, v2
	v_add_u32_e32 v2, v7, v2
	v_and_b32_e32 v3, 3, v7
	v_lshrrev_b32_e32 v9, 2, v2
	v_lshlrev_b32_e32 v11, 1, v2
	v_and_b32_e32 v1, 0xc0, v1
	s_ashr_i32 s6, s1, 6
	v_and_or_b32 v3, v2, s4, v3
	v_and_b32_e32 v9, 4, v9
	v_and_b32_e32 v11, 24, v11
	v_sub_u32_e32 v0, v0, v1
	s_ashr_i32 s0, s1, 8
	s_lshl_b32 s34, s6, 10
	v_or3_b32 v3, v3, v9, v11
	v_lshlrev_b32_e32 v9, 5, v8
	v_ashrrev_i16_sdwa v0, v222, sext(v0) dst_sel:DWORD dst_unused:UNUSED_PAD src0_sel:DWORD src1_sel:BYTE_0
	v_readlane_b32 s4, v255, 59
	v_and_b32_e32 v11, 32, v9
	v_bfe_i32 v9, v0, 0, 16
	v_readlane_b32 s5, v255, 60
	s_add_u32 s12, s29, s4
	v_add_lshl_u32 v0, v11, v9, 1
	s_addc_u32 s13, s30, s5
	s_add_i32 s35, s34, 0
	v_lshl_add_u32 v150, v3, 13, v0
	s_add_i32 m0, s35, 0x10000
	v_lshl_add_u32 v152, v2, 13, v0
	global_load_lds_dwordx4 v150, s[12:13]
	s_add_i32 m0, s35, 0x12000
	s_add_u32 s4, s12, 0x100000
	global_load_lds_dwordx4 v146, s[12:13]
	s_addc_u32 s5, s13, 0
	s_add_i32 m0, s35, 0x14000
	s_add_i32 s48, s35, 0x2000
	global_load_lds_dwordx4 v150, s[4:5]
	s_add_i32 m0, s35, 0x16000
	s_add_i32 s49, s35, 0x4000
	global_load_lds_dwordx4 v146, s[4:5]
	v_readlane_b32 s4, v255, 62
	s_mov_b32 m0, s35
	v_readlane_b32 s5, v255, 63
	s_add_i32 s52, s35, 0x6000
	v_mov_b32_e32 v151, v187
	v_mov_b32_e32 v147, v187
	s_cmp_eq_u32 s0, 1
	v_lshl_add_u64 v[0:1], s[12:13], 0, v[150:151]
	global_load_lds_dwordx4 v152, s[4:5]
	s_mov_b32 m0, s48
	v_lshl_add_u64 v[2:3], s[12:13], 0, v[146:147]
	global_load_lds_dwordx4 v148, s[4:5]
	v_readlane_b32 s4, v253, 0
	s_mov_b32 m0, s49
	v_readlane_b32 s5, v253, 1
	s_nop 4
	global_load_lds_dwordx4 v152, s[4:5]
	s_mov_b32 m0, s52
	s_nop 0
	global_load_lds_dwordx4 v148, s[4:5]
	s_cselect_b64 s[4:5], -1, 0
	s_cmp_lg_u32 s0, 1
	s_cbranch_scc1 .LBB0_701
	s_barrier
